# all six radix-16 FFT passes hand-written (LQ=6 and LQ=2 recompute twiddles)
# speedup vs baseline: 1.0150x; 1.0030x over previous
; template <bool INV> __device__ __forceinline__ void dft4(cf& a0, cf& a1, cf& a2, cf& a3) {
;     const cf t0 = cadd(a0, a2), t1 = csub(a0, a2), t2 = cadd(a1, a3), t3 = csub(a1, a3);
;     a0 = cadd(t0, t2); a2 = csub(t0, t2);
;     if (!INV) { a1 = {t1.x + t3.y, t1.y - t3.x}; a3 = {t1.x - t3.y, t1.y + t3.x}; }
;     else      { a1 = {t1.x - t3.y, t1.y + t3.x}; a3 = {t1.x + t3.y, t1.y - t3.x}; }
; }
; template <bool INV> __device__ __forceinline__ void dft16(cf (&a)[16]) {
; #pragma unroll
;     for (int n2 = 0; n2 < 4; ++n2) dft4<INV>(a[n2], a[4 + n2], a[8 + n2], a[12 + n2]);
; #pragma unroll
;     for (int k1 = 1; k1 < 4; ++k1)
; #pragma unroll
;         for (int n2 = 1; n2 < 4; ++n2) { const cf w = {W16C(n2 * k1), W16S(n2 * k1)};
;             a[4 * k1 + n2] = INV ? cmul(a[4 * k1 + n2], w) : cmulc(a[4 * k1 + n2], w); }
; #pragma unroll
;     for (int k1 = 0; k1 < 4; ++k1) dft4<INV>(a[4 * k1 + 0], a[4 * k1 + 1], a[4 * k1 + 2], a[4 * k1 + 3]);
; }
; template <bool INV, int LQ> __device__ __forceinline__ void fft_pass16(f32x2* X, int tid) {
;     constexpr int q = 1 << LQ, STR = q + 4 * (q >> 6);
; #pragma unroll 1
;     for (int gg = 0; gg < 2; ++gg) {
;         const int g = tid + 512 * gg, blk = g >> LQ, i = g & (q - 1), base = (blk << (LQ + 4)) + i;
;         f32x2* xb = X + fidx(base);
;         cf a[16];
; #pragma unroll
;         for (int j = 0; j < 16; ++j) { const f32x2 v = xb[j * STR]; a[j] = {v.x, v.y}; }
;         const float rev = (float)i * (1.f / (float)(16 << LQ));
;         const cf w1 = {__builtin_amdgcn_cosf(rev), __builtin_amdgcn_sinf(rev)};
;         if (!INV) {
;             dft16<false>(a);
;             cf w = w1;
; #pragma unroll
;             for (int k = 1; k < 16; ++k) { const int src = 4 * (k & 3) + (k >> 2);
;                 const cf y = cmulc(a[src], w); xb[k * STR] = (f32x2){y.x, y.y}; w = cmul(w, w1); }
.LBB0_281:
	v_add_u32_e32 v2, s93, v242
	v_lshrrev_b32_e32 v2, 4, v2
	v_and_b32_e32 v0, 63, v2
	v_lshrrev_b32_e32 v2, 6, v2
	v_lshl_add_u32 v1, v2, 10, v0
	v_lshrrev_b32_e32 v2, 6, v1
	v_lshl_add_u32 v1, v2, 2, v1
	v_lshlrev_b32_e32 v1, 3, v1
	ds_read_b64 v[10:11], v1
	ds_read_b64 v[12:13], v1 offset:544
	ds_read_b64 v[14:15], v1 offset:1088
	ds_read_b64 v[16:17], v1 offset:1632
	ds_read_b64 v[18:19], v1 offset:2176
	ds_read_b64 v[20:21], v1 offset:2720
	ds_read_b64 v[22:23], v1 offset:3264
	ds_read_b64 v[24:25], v1 offset:3808
	ds_read_b64 v[26:27], v1 offset:4352
	ds_read_b64 v[28:29], v1 offset:4896
	ds_read_b64 v[30:31], v1 offset:5440
	ds_read_b64 v[32:33], v1 offset:5984
	ds_read_b64 v[170:171], v1 offset:6528
	ds_read_b64 v[172:173], v1 offset:7072
	ds_read_b64 v[174:175], v1 offset:7616
	ds_read_b64 v[176:177], v1 offset:8160
	v_cvt_f32_u32_e32 v3, v0
	v_mul_f32_e32 v3, 0x3a800000, v3
	v_sin_f32_e32 v4, v3
	v_cos_f32_e32 v3, v3
	s_waitcnt lgkmcnt(0)
	v_add_f32_e32 v178, v10, v26
	v_add_f32_e32 v179, v11, v27
	v_sub_f32_e32 v180, v10, v26
	v_sub_f32_e32 v181, v11, v27
	v_add_f32_e32 v182, v18, v170
	v_add_f32_e32 v183, v19, v171
	v_sub_f32_e32 v184, v18, v170
	v_sub_f32_e32 v185, v19, v171
	v_add_f32_e32 v10, v178, v182
	v_add_f32_e32 v11, v179, v183
	v_sub_f32_e32 v26, v178, v182
	v_sub_f32_e32 v27, v179, v183
	v_add_f32_e32 v18, v180, v185
	v_sub_f32_e32 v19, v181, v184
	v_sub_f32_e32 v170, v180, v185
	v_add_f32_e32 v171, v181, v184
	v_add_f32_e32 v186, v12, v28
	v_add_f32_e32 v187, v13, v29
	v_sub_f32_e32 v188, v12, v28
	v_sub_f32_e32 v189, v13, v29
	v_add_f32_e32 v190, v20, v172
	v_add_f32_e32 v191, v21, v173
	v_sub_f32_e32 v192, v20, v172
	v_sub_f32_e32 v193, v21, v173
	v_add_f32_e32 v12, v186, v190
	v_add_f32_e32 v13, v187, v191
	v_sub_f32_e32 v28, v186, v190
	v_sub_f32_e32 v29, v187, v191
	v_add_f32_e32 v20, v188, v193
	v_sub_f32_e32 v21, v189, v192
	v_sub_f32_e32 v172, v188, v193
	v_add_f32_e32 v173, v189, v192
	v_add_f32_e32 v194, v14, v30
	v_add_f32_e32 v195, v15, v31
	v_sub_f32_e32 v196, v14, v30
	v_sub_f32_e32 v197, v15, v31
	v_add_f32_e32 v138, v22, v174
	v_add_f32_e32 v139, v23, v175
	v_sub_f32_e32 v140, v22, v174
	v_sub_f32_e32 v141, v23, v175
	v_add_f32_e32 v14, v194, v138
	v_add_f32_e32 v15, v195, v139
	v_sub_f32_e32 v30, v194, v138
	v_sub_f32_e32 v31, v195, v139
	v_add_f32_e32 v22, v196, v141
	v_sub_f32_e32 v23, v197, v140
	v_sub_f32_e32 v174, v196, v141
	v_add_f32_e32 v175, v197, v140
	v_add_f32_e32 v98, v16, v32
	v_add_f32_e32 v99, v17, v33
	v_sub_f32_e32 v178, v16, v32
	v_sub_f32_e32 v179, v17, v33
	v_add_f32_e32 v180, v24, v176
	v_add_f32_e32 v181, v25, v177
	v_sub_f32_e32 v182, v24, v176
	v_sub_f32_e32 v183, v25, v177
	v_add_f32_e32 v16, v98, v180
	v_add_f32_e32 v17, v99, v181
	v_sub_f32_e32 v32, v98, v180
	v_sub_f32_e32 v33, v99, v181
	v_add_f32_e32 v24, v178, v183
	v_sub_f32_e32 v25, v179, v182
	v_sub_f32_e32 v176, v178, v183
	v_add_f32_e32 v177, v179, v182
	v_mul_f32_e32 v184, s67, v20
	v_mul_f32_e32 v185, s67, v21
	v_fmac_f32_e32 v184, s66, v21
	v_fma_f32 v185, -v20, s66, v185
	v_add_f32_e32 v186, v22, v23
	v_sub_f32_e32 v187, v23, v22
	v_mul_f32_e32 v186, s70, v186
	v_mul_f32_e32 v187, s70, v187
	v_mul_f32_e32 v188, s66, v24
	v_mul_f32_e32 v189, s66, v25
	v_fmac_f32_e32 v188, s67, v25
	v_fma_f32 v189, -v24, s67, v189
	v_add_f32_e32 v190, v28, v29
	v_sub_f32_e32 v191, v29, v28
	v_mul_f32_e32 v190, s70, v190
	v_mul_f32_e32 v191, s70, v191
	v_mov_b32_e32 v192, v31
	v_xor_b32_e32 v193, 0x80000000, v30
	v_sub_f32_e32 v194, v33, v32
	v_add_f32_e32 v195, v32, v33
	v_mul_f32_e32 v194, s70, v194
	v_mul_f32_e32 v195, s71, v195
	v_mul_f32_e32 v196, s66, v172
	v_mul_f32_e32 v197, s66, v173
	v_fmac_f32_e32 v196, s67, v173
	v_fma_f32 v197, -v172, s67, v197
	v_sub_f32_e32 v138, v175, v174
	v_add_f32_e32 v139, v174, v175
	v_mul_f32_e32 v138, s70, v138
	v_mul_f32_e32 v139, s71, v139
	v_mul_f32_e32 v140, s67, v176
	v_mul_f32_e32 v141, s67, v177
	v_fmac_f32_e32 v140, s66, v177
	v_fma_f32 v141, -v176, s66, v141
	v_xor_b32_e32 v140, 0x80000000, v140
	v_xor_b32_e32 v141, 0x80000000, v141
	v_add_f32_e32 v98, v10, v14
	v_add_f32_e32 v99, v11, v15
	v_sub_f32_e32 v178, v10, v14
	v_sub_f32_e32 v179, v11, v15
	v_add_f32_e32 v180, v12, v16
	v_add_f32_e32 v181, v13, v17
	v_sub_f32_e32 v182, v12, v16
	v_sub_f32_e32 v183, v13, v17
	v_add_f32_e32 v10, v98, v180
	v_add_f32_e32 v11, v99, v181
	v_sub_f32_e32 v14, v98, v180
	v_sub_f32_e32 v15, v99, v181
	v_add_f32_e32 v12, v178, v183
	v_sub_f32_e32 v13, v179, v182
	v_sub_f32_e32 v16, v178, v183
	v_add_f32_e32 v17, v179, v182
	v_add_f32_e32 v20, v18, v186
	v_add_f32_e32 v21, v19, v187
	v_sub_f32_e32 v22, v18, v186
	v_sub_f32_e32 v23, v19, v187
	v_add_f32_e32 v24, v184, v188
	v_add_f32_e32 v25, v185, v189
	v_sub_f32_e32 v28, v184, v188
	v_sub_f32_e32 v29, v185, v189
	v_add_f32_e32 v18, v20, v24
	v_add_f32_e32 v19, v21, v25
	v_sub_f32_e32 v186, v20, v24
	v_sub_f32_e32 v187, v21, v25
	v_add_f32_e32 v184, v22, v29
	v_sub_f32_e32 v185, v23, v28
	v_sub_f32_e32 v188, v22, v29
	v_add_f32_e32 v189, v23, v28
	v_add_f32_e32 v30, v26, v192
	v_add_f32_e32 v31, v27, v193
	v_sub_f32_e32 v32, v26, v192
	v_sub_f32_e32 v33, v27, v193
	v_add_f32_e32 v172, v190, v194
	v_add_f32_e32 v173, v191, v195
	v_sub_f32_e32 v174, v190, v194
	v_sub_f32_e32 v175, v191, v195
	v_add_f32_e32 v26, v30, v172
	v_add_f32_e32 v27, v31, v173
	v_sub_f32_e32 v192, v30, v172
	v_sub_f32_e32 v193, v31, v173
	v_add_f32_e32 v190, v32, v175
	v_sub_f32_e32 v191, v33, v174
	v_sub_f32_e32 v194, v32, v175
	v_add_f32_e32 v195, v33, v174
	v_add_f32_e32 v176, v170, v138
	v_add_f32_e32 v177, v171, v139
	v_sub_f32_e32 v98, v170, v138
; template <bool INV> __device__ __forceinline__ void dft16(cf (&a)[16]) {
; #pragma unroll
;     for (int n2 = 0; n2 < 4; ++n2) dft4<INV>(a[n2], a[4 + n2], a[8 + n2], a[12 + n2]);
; #pragma unroll
;     for (int k1 = 1; k1 < 4; ++k1)
; #pragma unroll
;         for (int n2 = 1; n2 < 4; ++n2) { const cf w = {W16C(n2 * k1), W16S(n2 * k1)};
;             a[4 * k1 + n2] = INV ? cmul(a[4 * k1 + n2], w) : cmulc(a[4 * k1 + n2], w); }
; #pragma unroll
;     for (int k1 = 0; k1 < 4; ++k1) dft4<INV>(a[4 * k1 + 0], a[4 * k1 + 1], a[4 * k1 + 2], a[4 * k1 + 3]);
; }
; template <bool INV, int LQ> __device__ __forceinline__ void fft_pass16(f32x2* X, int tid) {
;     ...
;         if (!INV) {
;             dft16<false>(a);
;             cf w = w1;
; #pragma unroll
;             for (int k = 1; k < 16; ++k) { const int src = 4 * (k & 3) + (k >> 2);
;                 const cf y = cmulc(a[src], w); xb[k * STR] = (f32x2){y.x, y.y}; w = cmul(w, w1); }
;             xb[0] = (f32x2){a[0].x, a[0].y};
	v_sub_f32_e32 v99, v171, v139
	v_add_f32_e32 v178, v196, v140
	v_add_f32_e32 v179, v197, v141
	v_sub_f32_e32 v180, v196, v140
	v_sub_f32_e32 v181, v197, v141
	v_add_f32_e32 v170, v176, v178
	v_add_f32_e32 v171, v177, v179
	v_sub_f32_e32 v138, v176, v178
	v_sub_f32_e32 v139, v177, v179
	v_add_f32_e32 v196, v98, v181
	v_sub_f32_e32 v197, v99, v180
	v_sub_f32_e32 v140, v98, v181
	v_add_f32_e32 v141, v99, v180
	ds_write_b64 v1, v[10:11]
	v_mul_f32_e32 v182, v18, v3
	v_mul_f32_e32 v183, v19, v3
	v_fmac_f32_e32 v182, v19, v4
	v_fma_f32 v183, -v18, v4, v183
	ds_write_b64 v1, v[182:183] offset:544
	v_mul_f32_e32 v5, v3, v3
	v_mul_f32_e32 v6, v3, v4
	v_fma_f32 v5, -v4, v4, v5
	v_fmac_f32_e32 v6, v4, v3
	v_mul_f32_e32 v20, v26, v5
	v_mul_f32_e32 v21, v27, v5
	v_fmac_f32_e32 v20, v27, v6
	v_fma_f32 v21, -v26, v6, v21
	ds_write_b64 v1, v[20:21] offset:1088
	v_mul_f32_e32 v7, v5, v3
	v_mul_f32_e32 v8, v5, v4
	v_fma_f32 v7, -v6, v4, v7
	v_fmac_f32_e32 v8, v6, v3
	v_mul_f32_e32 v22, v170, v7
	v_mul_f32_e32 v23, v171, v7
	v_fmac_f32_e32 v22, v171, v8
	v_fma_f32 v23, -v170, v8, v23
	ds_write_b64 v1, v[22:23] offset:1632
	v_mul_f32_e32 v5, v7, v3
	v_mul_f32_e32 v6, v7, v4
	v_fma_f32 v5, -v8, v4, v5
	v_fmac_f32_e32 v6, v8, v3
	v_mul_f32_e32 v24, v12, v5
	v_mul_f32_e32 v25, v13, v5
	v_fmac_f32_e32 v24, v13, v6
	v_fma_f32 v25, -v12, v6, v25
	ds_write_b64 v1, v[24:25] offset:2176
	v_mul_f32_e32 v7, v5, v3
	v_mul_f32_e32 v8, v5, v4
	v_fma_f32 v7, -v6, v4, v7
	v_fmac_f32_e32 v8, v6, v3
	v_mul_f32_e32 v28, v184, v7
	v_mul_f32_e32 v29, v185, v7
	v_fmac_f32_e32 v28, v185, v8
	v_fma_f32 v29, -v184, v8, v29
	ds_write_b64 v1, v[28:29] offset:2720
	v_mul_f32_e32 v5, v7, v3
	v_mul_f32_e32 v6, v7, v4
	v_fma_f32 v5, -v8, v4, v5
	v_fmac_f32_e32 v6, v8, v3
	v_mul_f32_e32 v30, v190, v5
	v_mul_f32_e32 v31, v191, v5
	v_fmac_f32_e32 v30, v191, v6
	v_fma_f32 v31, -v190, v6, v31
	ds_write_b64 v1, v[30:31] offset:3264
	v_mul_f32_e32 v7, v5, v3
	v_mul_f32_e32 v8, v5, v4
	v_fma_f32 v7, -v6, v4, v7
	v_fmac_f32_e32 v8, v6, v3
	v_mul_f32_e32 v32, v196, v7
	v_mul_f32_e32 v33, v197, v7
	v_fmac_f32_e32 v32, v197, v8
	v_fma_f32 v33, -v196, v8, v33
	ds_write_b64 v1, v[32:33] offset:3808
	v_mul_f32_e32 v5, v7, v3
	v_mul_f32_e32 v6, v7, v4
	v_fma_f32 v5, -v8, v4, v5
	v_fmac_f32_e32 v6, v8, v3
	v_mul_f32_e32 v172, v14, v5
	v_mul_f32_e32 v173, v15, v5
	v_fmac_f32_e32 v172, v15, v6
	v_fma_f32 v173, -v14, v6, v173
	ds_write_b64 v1, v[172:173] offset:4352
	v_mul_f32_e32 v7, v5, v3
	v_mul_f32_e32 v8, v5, v4
	v_fma_f32 v7, -v6, v4, v7
	v_fmac_f32_e32 v8, v6, v3
	v_mul_f32_e32 v174, v186, v7
	v_mul_f32_e32 v175, v187, v7
	v_fmac_f32_e32 v174, v187, v8
	v_fma_f32 v175, -v186, v8, v175
	ds_write_b64 v1, v[174:175] offset:4896
	v_mul_f32_e32 v5, v7, v3
	v_mul_f32_e32 v6, v7, v4
	v_fma_f32 v5, -v8, v4, v5
	v_fmac_f32_e32 v6, v8, v3
	v_mul_f32_e32 v176, v192, v5
	v_mul_f32_e32 v177, v193, v5
	v_fmac_f32_e32 v176, v193, v6
	v_fma_f32 v177, -v192, v6, v177
	ds_write_b64 v1, v[176:177] offset:5440
	v_mul_f32_e32 v7, v5, v3
	v_mul_f32_e32 v8, v5, v4
	v_fma_f32 v7, -v6, v4, v7
	v_fmac_f32_e32 v8, v6, v3
	v_mul_f32_e32 v98, v138, v7
	v_mul_f32_e32 v99, v139, v7
	v_fmac_f32_e32 v98, v139, v8
	v_fma_f32 v99, -v138, v8, v99
	ds_write_b64 v1, v[98:99] offset:5984
	v_mul_f32_e32 v5, v7, v3
	v_mul_f32_e32 v6, v7, v4
	v_fma_f32 v5, -v8, v4, v5
	v_fmac_f32_e32 v6, v8, v3
	v_mul_f32_e32 v178, v16, v5
	v_mul_f32_e32 v179, v17, v5
	v_fmac_f32_e32 v178, v17, v6
	v_fma_f32 v179, -v16, v6, v179
	ds_write_b64 v1, v[178:179] offset:6528
	v_mul_f32_e32 v7, v5, v3
	v_mul_f32_e32 v8, v5, v4
	v_fma_f32 v7, -v6, v4, v7
	v_fmac_f32_e32 v8, v6, v3
	v_mul_f32_e32 v180, v188, v7
	v_mul_f32_e32 v181, v189, v7
	v_fmac_f32_e32 v180, v189, v8
	v_fma_f32 v181, -v188, v8, v181
	ds_write_b64 v1, v[180:181] offset:7072
	v_mul_f32_e32 v5, v7, v3
	v_mul_f32_e32 v6, v7, v4
	v_fma_f32 v5, -v8, v4, v5
	v_fmac_f32_e32 v6, v8, v3
	v_mul_f32_e32 v18, v194, v5
	v_mul_f32_e32 v19, v195, v5
	v_fmac_f32_e32 v18, v195, v6
	v_fma_f32 v19, -v194, v6, v19
	ds_write_b64 v1, v[18:19] offset:7616
	v_mul_f32_e32 v7, v5, v3
	v_mul_f32_e32 v8, v5, v4
	v_fma_f32 v7, -v6, v4, v7
	v_fmac_f32_e32 v8, v6, v3
	v_mul_f32_e32 v182, v140, v7
	v_mul_f32_e32 v183, v141, v7
	v_fmac_f32_e32 v182, v141, v8
	v_fma_f32 v183, -v140, v8, v183
	ds_write_b64 v1, v[182:183] offset:8160
	s_mov_b32 s64, s67
	s_mov_b32 s65, s66
	s_mov_b32 s48, s25
	s_mov_b32 s49, s71
	s_mov_b32 s24, s71
	s_mov_b32 s94, s70
	s_mov_b32 s95, s66
	s_mov_b32 s61, s71
	s_movk_i32 s93, 0x2000
	s_and_b64 vcc, exec, s[38:39]
	s_mov_b64 s[38:39], 0
	s_cbranch_vccnz .LBB0_281
	s_mov_b32 s93, 0
	s_mov_b64 s[38:39], -1
	s_waitcnt lgkmcnt(0)
	s_barrier
; template <bool INV> __device__ __forceinline__ void dft4(cf& a0, cf& a1, cf& a2, cf& a3) {
;     const cf t0 = cadd(a0, a2), t1 = csub(a0, a2), t2 = cadd(a1, a3), t3 = csub(a1, a3);
;     a0 = cadd(t0, t2); a2 = csub(t0, t2);
;     if (!INV) { a1 = {t1.x + t3.y, t1.y - t3.x}; a3 = {t1.x - t3.y, t1.y + t3.x}; }
;     else      { a1 = {t1.x - t3.y, t1.y + t3.x}; a3 = {t1.x + t3.y, t1.y - t3.x}; }
; }
; template <bool INV> __device__ __forceinline__ void dft16(cf (&a)[16]) {
; #pragma unroll
;     for (int n2 = 0; n2 < 4; ++n2) dft4<INV>(a[n2], a[4 + n2], a[8 + n2], a[12 + n2]);
; #pragma unroll
;     for (int k1 = 1; k1 < 4; ++k1)
; #pragma unroll
;         for (int n2 = 1; n2 < 4; ++n2) { const cf w = {W16C(n2 * k1), W16S(n2 * k1)};
;             a[4 * k1 + n2] = INV ? cmul(a[4 * k1 + n2], w) : cmulc(a[4 * k1 + n2], w); }
; #pragma unroll
;     for (int k1 = 0; k1 < 4; ++k1) dft4<INV>(a[4 * k1 + 0], a[4 * k1 + 1], a[4 * k1 + 2], a[4 * k1 + 3]);
; }
; template <bool INV, int LQ> __device__ __forceinline__ void fft_pass16(f32x2* X, int tid) {
;     constexpr int q = 1 << LQ, STR = q + 4 * (q >> 6);
; #pragma unroll 1
;     for (int gg = 0; gg < 2; ++gg) {
;         const int g = tid + 512 * gg, blk = g >> LQ, i = g & (q - 1), base = (blk << (LQ + 4)) + i;
;         f32x2* xb = X + fidx(base);
;         cf a[16];
; #pragma unroll
;         for (int j = 0; j < 16; ++j) { const f32x2 v = xb[j * STR]; a[j] = {v.x, v.y}; }
;         const float rev = (float)i * (1.f / (float)(16 << LQ));
;         const cf w1 = {__builtin_amdgcn_cosf(rev), __builtin_amdgcn_sinf(rev)};
;         if (!INV) {
;             dft16<false>(a);
;             cf w = w1;
; #pragma unroll
;             for (int k = 1; k < 16; ++k) { const int src = 4 * (k & 3) + (k >> 2);
;                 const cf y = cmulc(a[src], w); xb[k * STR] = (f32x2){y.x, y.y}; w = cmul(w, w1); }
.LBB0_283:
	v_add_u32_e32 v2, s93, v242
	v_lshrrev_b32_e32 v2, 4, v2
	v_and_b32_e32 v0, 3, v2
	v_lshrrev_b32_e32 v2, 2, v2
	v_lshl_add_u32 v1, v2, 6, v0
	v_lshrrev_b32_e32 v2, 6, v1
	v_lshl_add_u32 v1, v2, 2, v1
	v_lshlrev_b32_e32 v1, 3, v1
	ds_read_b64 v[10:11], v1
	ds_read_b64 v[12:13], v1 offset:32
	ds_read_b64 v[14:15], v1 offset:64
	ds_read_b64 v[16:17], v1 offset:96
	ds_read_b64 v[18:19], v1 offset:128
	ds_read_b64 v[20:21], v1 offset:160
	ds_read_b64 v[22:23], v1 offset:192
	ds_read_b64 v[24:25], v1 offset:224
	ds_read_b64 v[26:27], v1 offset:256
	ds_read_b64 v[28:29], v1 offset:288
	ds_read_b64 v[30:31], v1 offset:320
	ds_read_b64 v[32:33], v1 offset:352
	ds_read_b64 v[170:171], v1 offset:384
	ds_read_b64 v[172:173], v1 offset:416
	ds_read_b64 v[174:175], v1 offset:448
	ds_read_b64 v[176:177], v1 offset:480
	v_cvt_f32_u32_e32 v3, v0
	v_mul_f32_e32 v3, 0x3c800000, v3
	v_sin_f32_e32 v4, v3
	v_cos_f32_e32 v3, v3
	s_waitcnt lgkmcnt(0)
	v_add_f32_e32 v178, v10, v26
	v_add_f32_e32 v179, v11, v27
	v_sub_f32_e32 v180, v10, v26
	v_sub_f32_e32 v181, v11, v27
	v_add_f32_e32 v182, v18, v170
	v_add_f32_e32 v183, v19, v171
	v_sub_f32_e32 v184, v18, v170
	v_sub_f32_e32 v185, v19, v171
	v_add_f32_e32 v10, v178, v182
	v_add_f32_e32 v11, v179, v183
	v_sub_f32_e32 v26, v178, v182
	v_sub_f32_e32 v27, v179, v183
	v_add_f32_e32 v18, v180, v185
	v_sub_f32_e32 v19, v181, v184
	v_sub_f32_e32 v170, v180, v185
	v_add_f32_e32 v171, v181, v184
	v_add_f32_e32 v186, v12, v28
	v_add_f32_e32 v187, v13, v29
	v_sub_f32_e32 v188, v12, v28
	v_sub_f32_e32 v189, v13, v29
	v_add_f32_e32 v190, v20, v172
	v_add_f32_e32 v191, v21, v173
	v_sub_f32_e32 v192, v20, v172
	v_sub_f32_e32 v193, v21, v173
	v_add_f32_e32 v12, v186, v190
	v_add_f32_e32 v13, v187, v191
	v_sub_f32_e32 v28, v186, v190
	v_sub_f32_e32 v29, v187, v191
	v_add_f32_e32 v20, v188, v193
	v_sub_f32_e32 v21, v189, v192
	v_sub_f32_e32 v172, v188, v193
	v_add_f32_e32 v173, v189, v192
	v_add_f32_e32 v194, v14, v30
	v_add_f32_e32 v195, v15, v31
	v_sub_f32_e32 v196, v14, v30
	v_sub_f32_e32 v197, v15, v31
	v_add_f32_e32 v138, v22, v174
	v_add_f32_e32 v139, v23, v175
	v_sub_f32_e32 v140, v22, v174
	v_sub_f32_e32 v141, v23, v175
	v_add_f32_e32 v14, v194, v138
	v_add_f32_e32 v15, v195, v139
	v_sub_f32_e32 v30, v194, v138
	v_sub_f32_e32 v31, v195, v139
	v_add_f32_e32 v22, v196, v141
	v_sub_f32_e32 v23, v197, v140
	v_sub_f32_e32 v174, v196, v141
	v_add_f32_e32 v175, v197, v140
	v_add_f32_e32 v98, v16, v32
	v_add_f32_e32 v99, v17, v33
	v_sub_f32_e32 v178, v16, v32
	v_sub_f32_e32 v179, v17, v33
	v_add_f32_e32 v180, v24, v176
	v_add_f32_e32 v181, v25, v177
	v_sub_f32_e32 v182, v24, v176
	v_sub_f32_e32 v183, v25, v177
	v_add_f32_e32 v16, v98, v180
	v_add_f32_e32 v17, v99, v181
	v_sub_f32_e32 v32, v98, v180
	v_sub_f32_e32 v33, v99, v181
	v_add_f32_e32 v24, v178, v183
	v_sub_f32_e32 v25, v179, v182
	v_sub_f32_e32 v176, v178, v183
	v_add_f32_e32 v177, v179, v182
	v_mul_f32_e32 v184, s67, v20
	v_mul_f32_e32 v185, s67, v21
	v_fmac_f32_e32 v184, s66, v21
	v_fma_f32 v185, -v20, s66, v185
	v_add_f32_e32 v186, v22, v23
	v_sub_f32_e32 v187, v23, v22
	v_mul_f32_e32 v186, s70, v186
	v_mul_f32_e32 v187, s70, v187
	v_mul_f32_e32 v188, s66, v24
	v_mul_f32_e32 v189, s66, v25
	v_fmac_f32_e32 v188, s67, v25
	v_fma_f32 v189, -v24, s67, v189
	v_add_f32_e32 v190, v28, v29
	v_sub_f32_e32 v191, v29, v28
	v_mul_f32_e32 v190, s70, v190
	v_mul_f32_e32 v191, s70, v191
	v_mov_b32_e32 v192, v31
	v_xor_b32_e32 v193, 0x80000000, v30
	v_sub_f32_e32 v194, v33, v32
	v_add_f32_e32 v195, v32, v33
	v_mul_f32_e32 v194, s70, v194
	v_mul_f32_e32 v195, s71, v195
	v_mul_f32_e32 v196, s66, v172
	v_mul_f32_e32 v197, s66, v173
	v_fmac_f32_e32 v196, s67, v173
	v_fma_f32 v197, -v172, s67, v197
	v_sub_f32_e32 v138, v175, v174
	v_add_f32_e32 v139, v174, v175
	v_mul_f32_e32 v138, s70, v138
	v_mul_f32_e32 v139, s71, v139
	v_mul_f32_e32 v140, s67, v176
	v_mul_f32_e32 v141, s67, v177
	v_fmac_f32_e32 v140, s66, v177
	v_fma_f32 v141, -v176, s66, v141
	v_xor_b32_e32 v140, 0x80000000, v140
	v_xor_b32_e32 v141, 0x80000000, v141
	v_add_f32_e32 v98, v10, v14
	v_add_f32_e32 v99, v11, v15
	v_sub_f32_e32 v178, v10, v14
	v_sub_f32_e32 v179, v11, v15
	v_add_f32_e32 v180, v12, v16
	v_add_f32_e32 v181, v13, v17
	v_sub_f32_e32 v182, v12, v16
	v_sub_f32_e32 v183, v13, v17
	v_add_f32_e32 v10, v98, v180
	v_add_f32_e32 v11, v99, v181
	v_sub_f32_e32 v14, v98, v180
	v_sub_f32_e32 v15, v99, v181
	v_add_f32_e32 v12, v178, v183
	v_sub_f32_e32 v13, v179, v182
	v_sub_f32_e32 v16, v178, v183
	v_add_f32_e32 v17, v179, v182
	v_add_f32_e32 v20, v18, v186
	v_add_f32_e32 v21, v19, v187
	v_sub_f32_e32 v22, v18, v186
	v_sub_f32_e32 v23, v19, v187
	v_add_f32_e32 v24, v184, v188
	v_add_f32_e32 v25, v185, v189
	v_sub_f32_e32 v28, v184, v188
	v_sub_f32_e32 v29, v185, v189
	v_add_f32_e32 v18, v20, v24
	v_add_f32_e32 v19, v21, v25
	v_sub_f32_e32 v186, v20, v24
	v_sub_f32_e32 v187, v21, v25
	v_add_f32_e32 v184, v22, v29
	v_sub_f32_e32 v185, v23, v28
	v_sub_f32_e32 v188, v22, v29
	v_add_f32_e32 v189, v23, v28
	v_add_f32_e32 v30, v26, v192
	v_add_f32_e32 v31, v27, v193
	v_sub_f32_e32 v32, v26, v192
	v_sub_f32_e32 v33, v27, v193
	v_add_f32_e32 v172, v190, v194
	v_add_f32_e32 v173, v191, v195
; template <bool INV, int LQ> __device__ __forceinline__ void fft_pass16(f32x2* X, int tid) {
;     ...
;         if (!INV) {
;             dft16<false>(a);
;             cf w = w1;
; #pragma unroll
;             for (int k = 1; k < 16; ++k) { const int src = 4 * (k & 3) + (k >> 2);
;                 const cf y = cmulc(a[src], w); xb[k * STR] = (f32x2){y.x, y.y}; w = cmul(w, w1); }
;             xb[0] = (f32x2){a[0].x, a[0].y};
; __device__ __forceinline__ void hyena_channel(const Params& p, int l, int c, unsigned char* lds, int wid0) {
;     ...
;         fft_pass16<false, 2>(X, tid); __syncthreads();
;         if (it == 0) {
	v_sub_f32_e32 v174, v190, v194
	v_sub_f32_e32 v175, v191, v195
	v_add_f32_e32 v26, v30, v172
	v_add_f32_e32 v27, v31, v173
	v_sub_f32_e32 v192, v30, v172
	v_sub_f32_e32 v193, v31, v173
	v_add_f32_e32 v190, v32, v175
	v_sub_f32_e32 v191, v33, v174
	v_sub_f32_e32 v194, v32, v175
	v_add_f32_e32 v195, v33, v174
	v_add_f32_e32 v176, v170, v138
	v_add_f32_e32 v177, v171, v139
	v_sub_f32_e32 v98, v170, v138
	v_sub_f32_e32 v99, v171, v139
	v_add_f32_e32 v178, v196, v140
	v_add_f32_e32 v179, v197, v141
	v_sub_f32_e32 v180, v196, v140
	v_sub_f32_e32 v181, v197, v141
	v_add_f32_e32 v170, v176, v178
	v_add_f32_e32 v171, v177, v179
	v_sub_f32_e32 v138, v176, v178
	v_sub_f32_e32 v139, v177, v179
	v_add_f32_e32 v196, v98, v181
	v_sub_f32_e32 v197, v99, v180
	v_sub_f32_e32 v140, v98, v181
	v_add_f32_e32 v141, v99, v180
	ds_write_b64 v1, v[10:11]
	v_mul_f32_e32 v182, v18, v3
	v_mul_f32_e32 v183, v19, v3
	v_fmac_f32_e32 v182, v19, v4
	v_fma_f32 v183, -v18, v4, v183
	ds_write_b64 v1, v[182:183] offset:32
	v_mul_f32_e32 v5, v3, v3
	v_mul_f32_e32 v6, v3, v4
	v_fma_f32 v5, -v4, v4, v5
	v_fmac_f32_e32 v6, v4, v3
	v_mul_f32_e32 v20, v26, v5
	v_mul_f32_e32 v21, v27, v5
	v_fmac_f32_e32 v20, v27, v6
	v_fma_f32 v21, -v26, v6, v21
	ds_write_b64 v1, v[20:21] offset:64
	v_mul_f32_e32 v7, v5, v3
	v_mul_f32_e32 v8, v5, v4
	v_fma_f32 v7, -v6, v4, v7
	v_fmac_f32_e32 v8, v6, v3
	v_mul_f32_e32 v22, v170, v7
	v_mul_f32_e32 v23, v171, v7
	v_fmac_f32_e32 v22, v171, v8
	v_fma_f32 v23, -v170, v8, v23
	ds_write_b64 v1, v[22:23] offset:96
	v_mul_f32_e32 v5, v7, v3
	v_mul_f32_e32 v6, v7, v4
	v_fma_f32 v5, -v8, v4, v5
	v_fmac_f32_e32 v6, v8, v3
	v_mul_f32_e32 v24, v12, v5
	v_mul_f32_e32 v25, v13, v5
	v_fmac_f32_e32 v24, v13, v6
	v_fma_f32 v25, -v12, v6, v25
	ds_write_b64 v1, v[24:25] offset:128
	v_mul_f32_e32 v7, v5, v3
	v_mul_f32_e32 v8, v5, v4
	v_fma_f32 v7, -v6, v4, v7
	v_fmac_f32_e32 v8, v6, v3
	v_mul_f32_e32 v28, v184, v7
	v_mul_f32_e32 v29, v185, v7
	v_fmac_f32_e32 v28, v185, v8
	v_fma_f32 v29, -v184, v8, v29
	ds_write_b64 v1, v[28:29] offset:160
	v_mul_f32_e32 v5, v7, v3
	v_mul_f32_e32 v6, v7, v4
	v_fma_f32 v5, -v8, v4, v5
	v_fmac_f32_e32 v6, v8, v3
	v_mul_f32_e32 v30, v190, v5
	v_mul_f32_e32 v31, v191, v5
	v_fmac_f32_e32 v30, v191, v6
	v_fma_f32 v31, -v190, v6, v31
	ds_write_b64 v1, v[30:31] offset:192
	v_mul_f32_e32 v7, v5, v3
	v_mul_f32_e32 v8, v5, v4
	v_fma_f32 v7, -v6, v4, v7
	v_fmac_f32_e32 v8, v6, v3
	v_mul_f32_e32 v32, v196, v7
	v_mul_f32_e32 v33, v197, v7
	v_fmac_f32_e32 v32, v197, v8
	v_fma_f32 v33, -v196, v8, v33
	ds_write_b64 v1, v[32:33] offset:224
	v_mul_f32_e32 v5, v7, v3
	v_mul_f32_e32 v6, v7, v4
	v_fma_f32 v5, -v8, v4, v5
	v_fmac_f32_e32 v6, v8, v3
	v_mul_f32_e32 v172, v14, v5
	v_mul_f32_e32 v173, v15, v5
	v_fmac_f32_e32 v172, v15, v6
	v_fma_f32 v173, -v14, v6, v173
	ds_write_b64 v1, v[172:173] offset:256
	v_mul_f32_e32 v7, v5, v3
	v_mul_f32_e32 v8, v5, v4
	v_fma_f32 v7, -v6, v4, v7
	v_fmac_f32_e32 v8, v6, v3
	v_mul_f32_e32 v174, v186, v7
	v_mul_f32_e32 v175, v187, v7
	v_fmac_f32_e32 v174, v187, v8
	v_fma_f32 v175, -v186, v8, v175
	ds_write_b64 v1, v[174:175] offset:288
	v_mul_f32_e32 v5, v7, v3
	v_mul_f32_e32 v6, v7, v4
	v_fma_f32 v5, -v8, v4, v5
	v_fmac_f32_e32 v6, v8, v3
	v_mul_f32_e32 v176, v192, v5
	v_mul_f32_e32 v177, v193, v5
	v_fmac_f32_e32 v176, v193, v6
	v_fma_f32 v177, -v192, v6, v177
	ds_write_b64 v1, v[176:177] offset:320
	v_mul_f32_e32 v7, v5, v3
	v_mul_f32_e32 v8, v5, v4
	v_fma_f32 v7, -v6, v4, v7
	v_fmac_f32_e32 v8, v6, v3
	v_mul_f32_e32 v98, v138, v7
	v_mul_f32_e32 v99, v139, v7
	v_fmac_f32_e32 v98, v139, v8
	v_fma_f32 v99, -v138, v8, v99
	ds_write_b64 v1, v[98:99] offset:352
	v_mul_f32_e32 v5, v7, v3
	v_mul_f32_e32 v6, v7, v4
	v_fma_f32 v5, -v8, v4, v5
	v_fmac_f32_e32 v6, v8, v3
	v_mul_f32_e32 v178, v16, v5
	v_mul_f32_e32 v179, v17, v5
	v_fmac_f32_e32 v178, v17, v6
	v_fma_f32 v179, -v16, v6, v179
	ds_write_b64 v1, v[178:179] offset:384
	v_mul_f32_e32 v7, v5, v3
	v_mul_f32_e32 v8, v5, v4
	v_fma_f32 v7, -v6, v4, v7
	v_fmac_f32_e32 v8, v6, v3
	v_mul_f32_e32 v180, v188, v7
	v_mul_f32_e32 v181, v189, v7
	v_fmac_f32_e32 v180, v189, v8
	v_fma_f32 v181, -v188, v8, v181
	ds_write_b64 v1, v[180:181] offset:416
	v_mul_f32_e32 v5, v7, v3
	v_mul_f32_e32 v6, v7, v4
	v_fma_f32 v5, -v8, v4, v5
	v_fmac_f32_e32 v6, v8, v3
	v_mul_f32_e32 v18, v194, v5
	v_mul_f32_e32 v19, v195, v5
	v_fmac_f32_e32 v18, v195, v6
	v_fma_f32 v19, -v194, v6, v19
	ds_write_b64 v1, v[18:19] offset:448
	v_mul_f32_e32 v7, v5, v3
	v_mul_f32_e32 v8, v5, v4
	v_fma_f32 v7, -v6, v4, v7
	v_fmac_f32_e32 v8, v6, v3
	v_mul_f32_e32 v182, v140, v7
	v_mul_f32_e32 v183, v141, v7
	v_fmac_f32_e32 v182, v141, v8
	v_fma_f32 v183, -v140, v8, v183
	ds_write_b64 v1, v[182:183] offset:480
	s_mov_b32 s64, s67
	s_mov_b32 s65, s66
	s_mov_b32 s48, s25
	s_mov_b32 s49, s71
	s_mov_b32 s24, s71
	s_mov_b32 s94, s70
	s_mov_b32 s95, s66
	s_mov_b32 s61, s71
	s_movk_i32 s93, 0x2000
	s_and_b64 vcc, exec, s[38:39]
	s_mov_b64 s[38:39], 0
	s_cbranch_vccnz .LBB0_283
	v_cndmask_b32_e64 v0, 0, 1, s[0:1]
	v_cmp_ne_u32_e64 s[38:39], 1, v0
	s_andn2_b64 vcc, exec, s[0:1]
	s_mov_b64 s[0:1], -1
	s_mov_b32 s61, s79
	s_waitcnt lgkmcnt(0)
	s_barrier
	s_cbranch_vccnz .LBB0_288
	s_mov_b32 s0, 0
	v_mov_b32_e32 v0, v245

; template <bool INV> __device__ __forceinline__ void dft4(cf& a0, cf& a1, cf& a2, cf& a3) {
;     const cf t0 = cadd(a0, a2), t1 = csub(a0, a2), t2 = cadd(a1, a3), t3 = csub(a1, a3);
;     a0 = cadd(t0, t2); a2 = csub(t0, t2);
;     if (!INV) { a1 = {t1.x + t3.y, t1.y - t3.x}; a3 = {t1.x - t3.y, t1.y + t3.x}; }
;     else      { a1 = {t1.x - t3.y, t1.y + t3.x}; a3 = {t1.x + t3.y, t1.y - t3.x}; }
; }
; template <bool INV> __device__ __forceinline__ void dft16(cf (&a)[16]) {
; #pragma unroll
;     for (int n2 = 0; n2 < 4; ++n2) dft4<INV>(a[n2], a[4 + n2], a[8 + n2], a[12 + n2]);
; #pragma unroll
;     for (int k1 = 1; k1 < 4; ++k1)
; #pragma unroll
;         for (int n2 = 1; n2 < 4; ++n2) { const cf w = {W16C(n2 * k1), W16S(n2 * k1)};
;             a[4 * k1 + n2] = INV ? cmul(a[4 * k1 + n2], w) : cmulc(a[4 * k1 + n2], w); }
; #pragma unroll
;     for (int k1 = 0; k1 < 4; ++k1) dft4<INV>(a[4 * k1 + 0], a[4 * k1 + 1], a[4 * k1 + 2], a[4 * k1 + 3]);
; }
; template <bool INV, int LQ> __device__ __forceinline__ void fft_pass16(f32x2* X, int tid) {
;     ...
;         } else {
;             cf w = w1;
; #pragma unroll
;             for (int k = 1; k < 16; ++k) { a[k] = cmul(a[k], w); w = cmul(w, w1); }
;             dft16<true>(a);
; #pragma unroll
;             for (int k = 0; k < 16; ++k) { const int src = 4 * (k & 3) + (k >> 2); xb[k * STR] = (f32x2){a[src].x, a[src].y}; }
;         }
.LBB0_292:
	v_add_u32_e32 v2, s24, v242
	v_lshrrev_b32_e32 v2, 4, v2
	v_and_b32_e32 v0, 3, v2
	v_lshrrev_b32_e32 v2, 2, v2
	v_lshl_add_u32 v1, v2, 6, v0
	v_lshrrev_b32_e32 v2, 6, v1
	v_lshl_add_u32 v1, v2, 2, v1
	v_lshlrev_b32_e32 v1, 3, v1
	ds_read_b64 v[10:11], v1
	ds_read_b64 v[12:13], v1 offset:32
	ds_read_b64 v[14:15], v1 offset:64
	ds_read_b64 v[16:17], v1 offset:96
	ds_read_b64 v[18:19], v1 offset:128
	ds_read_b64 v[20:21], v1 offset:160
	ds_read_b64 v[22:23], v1 offset:192
	ds_read_b64 v[24:25], v1 offset:224
	ds_read_b64 v[26:27], v1 offset:256
	ds_read_b64 v[28:29], v1 offset:288
	ds_read_b64 v[30:31], v1 offset:320
	ds_read_b64 v[32:33], v1 offset:352
	ds_read_b64 v[170:171], v1 offset:384
	ds_read_b64 v[172:173], v1 offset:416
	ds_read_b64 v[174:175], v1 offset:448
	ds_read_b64 v[176:177], v1 offset:480
	v_cvt_f32_u32_e32 v3, v0
	v_mul_f32_e32 v3, 0x3c800000, v3
	v_sin_f32_e32 v4, v3
	v_cos_f32_e32 v3, v3
	s_waitcnt lgkmcnt(0)
	v_mul_f32_e32 v178, v12, v3
	v_mul_f32_e32 v179, v12, v4
	v_fma_f32 v178, -v13, v4, v178
	v_fmac_f32_e32 v179, v13, v3
	v_mul_f32_e32 v5, v3, v3
	v_mul_f32_e32 v6, v3, v4
	v_fma_f32 v5, -v4, v4, v5
	v_fmac_f32_e32 v6, v4, v3
	v_mul_f32_e32 v180, v14, v5
	v_mul_f32_e32 v181, v14, v6
	v_fma_f32 v180, -v15, v6, v180
	v_fmac_f32_e32 v181, v15, v5
	v_mul_f32_e32 v7, v5, v3
	v_mul_f32_e32 v8, v5, v4
	v_fma_f32 v7, -v6, v4, v7
	v_fmac_f32_e32 v8, v6, v3
	v_mul_f32_e32 v182, v16, v7
	v_mul_f32_e32 v183, v16, v8
	v_fma_f32 v182, -v17, v8, v182
	v_fmac_f32_e32 v183, v17, v7
	v_mul_f32_e32 v5, v7, v3
	v_mul_f32_e32 v6, v7, v4
	v_fma_f32 v5, -v8, v4, v5
	v_fmac_f32_e32 v6, v8, v3
	v_mul_f32_e32 v184, v18, v5
	v_mul_f32_e32 v185, v18, v6
	v_fma_f32 v184, -v19, v6, v184
	v_fmac_f32_e32 v185, v19, v5
	v_mul_f32_e32 v7, v5, v3
	v_mul_f32_e32 v8, v5, v4
	v_fma_f32 v7, -v6, v4, v7
	v_fmac_f32_e32 v8, v6, v3
	v_mul_f32_e32 v186, v20, v7
	v_mul_f32_e32 v187, v20, v8
	v_fma_f32 v186, -v21, v8, v186
	v_fmac_f32_e32 v187, v21, v7
	v_mul_f32_e32 v5, v7, v3
	v_mul_f32_e32 v6, v7, v4
	v_fma_f32 v5, -v8, v4, v5
	v_fmac_f32_e32 v6, v8, v3
	v_mul_f32_e32 v188, v22, v5
	v_mul_f32_e32 v189, v22, v6
	v_fma_f32 v188, -v23, v6, v188
	v_fmac_f32_e32 v189, v23, v5
	v_mul_f32_e32 v7, v5, v3
	v_mul_f32_e32 v8, v5, v4
	v_fma_f32 v7, -v6, v4, v7
	v_fmac_f32_e32 v8, v6, v3
	v_mul_f32_e32 v190, v24, v7
	v_mul_f32_e32 v191, v24, v8
	v_fma_f32 v190, -v25, v8, v190
	v_fmac_f32_e32 v191, v25, v7
	v_mul_f32_e32 v5, v7, v3
	v_mul_f32_e32 v6, v7, v4
	v_fma_f32 v5, -v8, v4, v5
	v_fmac_f32_e32 v6, v8, v3
	v_mul_f32_e32 v192, v26, v5
	v_mul_f32_e32 v193, v26, v6
	v_fma_f32 v192, -v27, v6, v192
	v_fmac_f32_e32 v193, v27, v5
	v_mul_f32_e32 v7, v5, v3
	v_mul_f32_e32 v8, v5, v4
	v_fma_f32 v7, -v6, v4, v7
	v_fmac_f32_e32 v8, v6, v3
	v_mul_f32_e32 v194, v28, v7
	v_mul_f32_e32 v195, v28, v8
	v_fma_f32 v194, -v29, v8, v194
	v_fmac_f32_e32 v195, v29, v7
	v_mul_f32_e32 v5, v7, v3
	v_mul_f32_e32 v6, v7, v4
	v_fma_f32 v5, -v8, v4, v5
	v_fmac_f32_e32 v6, v8, v3
	v_mul_f32_e32 v196, v30, v5
	v_mul_f32_e32 v197, v30, v6
	v_fma_f32 v196, -v31, v6, v196
	v_fmac_f32_e32 v197, v31, v5
	v_mul_f32_e32 v7, v5, v3
	v_mul_f32_e32 v8, v5, v4
	v_fma_f32 v7, -v6, v4, v7
	v_fmac_f32_e32 v8, v6, v3
	v_mul_f32_e32 v138, v32, v7
	v_mul_f32_e32 v139, v32, v8
	v_fma_f32 v138, -v33, v8, v138
	v_fmac_f32_e32 v139, v33, v7
	v_mul_f32_e32 v5, v7, v3
	v_mul_f32_e32 v6, v7, v4
	v_fma_f32 v5, -v8, v4, v5
	v_fmac_f32_e32 v6, v8, v3
	v_mul_f32_e32 v140, v170, v5
	v_mul_f32_e32 v141, v170, v6
	v_fma_f32 v140, -v171, v6, v140
	v_fmac_f32_e32 v141, v171, v5
	v_mul_f32_e32 v7, v5, v3
	v_mul_f32_e32 v8, v5, v4
	v_fma_f32 v7, -v6, v4, v7
	v_fmac_f32_e32 v8, v6, v3
	v_mul_f32_e32 v98, v172, v7
	v_mul_f32_e32 v99, v172, v8
	v_fma_f32 v98, -v173, v8, v98
	v_fmac_f32_e32 v99, v173, v7
	v_mul_f32_e32 v5, v7, v3
	v_mul_f32_e32 v6, v7, v4
	v_fma_f32 v5, -v8, v4, v5
	v_fmac_f32_e32 v6, v8, v3
	v_mul_f32_e32 v12, v174, v5
	v_mul_f32_e32 v13, v174, v6
	v_fma_f32 v12, -v175, v6, v12
	v_fmac_f32_e32 v13, v175, v5
	v_mul_f32_e32 v7, v5, v3
	v_mul_f32_e32 v8, v5, v4
	v_fma_f32 v7, -v6, v4, v7
	v_fmac_f32_e32 v8, v6, v3
	v_mul_f32_e32 v14, v176, v7
	v_mul_f32_e32 v15, v176, v8
	v_fma_f32 v14, -v177, v8, v14
	v_fmac_f32_e32 v15, v177, v7
	v_add_f32_e32 v16, v10, v192
	v_add_f32_e32 v17, v11, v193
	v_sub_f32_e32 v18, v10, v192
	v_sub_f32_e32 v19, v11, v193
	v_add_f32_e32 v20, v184, v140
	v_add_f32_e32 v21, v185, v141
	v_sub_f32_e32 v22, v184, v140
	v_sub_f32_e32 v23, v185, v141
	v_add_f32_e32 v10, v16, v20
	v_add_f32_e32 v11, v17, v21
	v_sub_f32_e32 v192, v16, v20
	v_sub_f32_e32 v193, v17, v21
	v_sub_f32_e32 v184, v18, v23
	v_add_f32_e32 v185, v19, v22
	v_add_f32_e32 v140, v18, v23
	v_sub_f32_e32 v141, v19, v22
	v_add_f32_e32 v24, v178, v194
	v_add_f32_e32 v25, v179, v195
	v_sub_f32_e32 v26, v178, v194
	v_sub_f32_e32 v27, v179, v195
	v_add_f32_e32 v28, v186, v98
	v_add_f32_e32 v29, v187, v99
	v_sub_f32_e32 v30, v186, v98
	v_sub_f32_e32 v31, v187, v99
	v_add_f32_e32 v178, v24, v28
	v_add_f32_e32 v179, v25, v29
	v_sub_f32_e32 v194, v24, v28
	v_sub_f32_e32 v195, v25, v29
	v_sub_f32_e32 v186, v26, v31
	v_add_f32_e32 v187, v27, v30
	v_add_f32_e32 v98, v26, v31
	v_sub_f32_e32 v99, v27, v30
	v_add_f32_e32 v32, v180, v196
	v_add_f32_e32 v33, v181, v197
	v_sub_f32_e32 v170, v180, v196
	v_sub_f32_e32 v171, v181, v197
	v_add_f32_e32 v172, v188, v12
	v_add_f32_e32 v173, v189, v13
	v_sub_f32_e32 v174, v188, v12
	v_sub_f32_e32 v175, v189, v13
	v_add_f32_e32 v180, v32, v172
	v_add_f32_e32 v181, v33, v173
	v_sub_f32_e32 v196, v32, v172
	v_sub_f32_e32 v197, v33, v173
	v_sub_f32_e32 v188, v170, v175
	v_add_f32_e32 v189, v171, v174
; template <bool INV> __device__ __forceinline__ void dft16(cf (&a)[16]) {
; #pragma unroll
;     for (int n2 = 0; n2 < 4; ++n2) dft4<INV>(a[n2], a[4 + n2], a[8 + n2], a[12 + n2]);
; #pragma unroll
;     for (int k1 = 1; k1 < 4; ++k1)
; #pragma unroll
;         for (int n2 = 1; n2 < 4; ++n2) { const cf w = {W16C(n2 * k1), W16S(n2 * k1)};
;             a[4 * k1 + n2] = INV ? cmul(a[4 * k1 + n2], w) : cmulc(a[4 * k1 + n2], w); }
; #pragma unroll
;     for (int k1 = 0; k1 < 4; ++k1) dft4<INV>(a[4 * k1 + 0], a[4 * k1 + 1], a[4 * k1 + 2], a[4 * k1 + 3]);
; }
; template <bool INV, int LQ> __device__ __forceinline__ void fft_pass16(f32x2* X, int tid) {
;     ...
;         } else {
;             cf w = w1;
; #pragma unroll
;             for (int k = 1; k < 16; ++k) { a[k] = cmul(a[k], w); w = cmul(w, w1); }
;             dft16<true>(a);
; #pragma unroll
;             for (int k = 0; k < 16; ++k) { const int src = 4 * (k & 3) + (k >> 2); xb[k * STR] = (f32x2){a[src].x, a[src].y}; }
;         }
	v_add_f32_e32 v12, v170, v175
	v_sub_f32_e32 v13, v171, v174
	v_add_f32_e32 v176, v182, v138
	v_add_f32_e32 v177, v183, v139
	v_sub_f32_e32 v16, v182, v138
	v_sub_f32_e32 v17, v183, v139
	v_add_f32_e32 v18, v190, v14
	v_add_f32_e32 v19, v191, v15
	v_sub_f32_e32 v20, v190, v14
	v_sub_f32_e32 v21, v191, v15
	v_add_f32_e32 v182, v176, v18
	v_add_f32_e32 v183, v177, v19
	v_sub_f32_e32 v138, v176, v18
	v_sub_f32_e32 v139, v177, v19
	v_sub_f32_e32 v190, v16, v21
	v_add_f32_e32 v191, v17, v20
	v_add_f32_e32 v14, v16, v21
	v_sub_f32_e32 v15, v17, v20
	v_mul_f32_e32 v22, s67, v186
	v_mul_f32_e32 v23, s67, v187
	v_fma_f32 v22, -v187, s66, v22
	v_fmac_f32_e32 v23, s66, v186
	v_sub_f32_e32 v24, v188, v189
	v_add_f32_e32 v25, v188, v189
	v_mul_f32_e32 v24, s70, v24
	v_mul_f32_e32 v25, s70, v25
	v_mul_f32_e32 v26, s66, v190
	v_mul_f32_e32 v27, s66, v191
	v_fma_f32 v26, -v191, s67, v26
	v_fmac_f32_e32 v27, s67, v190
	v_sub_f32_e32 v28, v194, v195
	v_add_f32_e32 v29, v194, v195
	v_mul_f32_e32 v28, s70, v28
	v_mul_f32_e32 v29, s70, v29
	v_xor_b32_e32 v30, 0x80000000, v197
	v_mov_b32_e32 v31, v196
	v_add_f32_e32 v32, v138, v139
	v_sub_f32_e32 v33, v138, v139
	v_mul_f32_e32 v32, s71, v32
	v_mul_f32_e32 v33, s70, v33
	v_mul_f32_e32 v170, s66, v98
	v_mul_f32_e32 v171, s66, v99
	v_fma_f32 v170, -v99, s67, v170
	v_fmac_f32_e32 v171, s67, v98
	v_add_f32_e32 v172, v12, v13
	v_sub_f32_e32 v173, v12, v13
	v_mul_f32_e32 v172, s71, v172
	v_mul_f32_e32 v173, s70, v173
	v_mul_f32_e32 v174, s67, v14
	v_mul_f32_e32 v175, s67, v15
	v_fma_f32 v174, -v15, s66, v174
	v_fmac_f32_e32 v175, s66, v14
	v_xor_b32_e32 v174, 0x80000000, v174
	v_xor_b32_e32 v175, 0x80000000, v175
	v_add_f32_e32 v176, v10, v180
	v_add_f32_e32 v177, v11, v181
	v_sub_f32_e32 v16, v10, v180
	v_sub_f32_e32 v17, v11, v181
	v_add_f32_e32 v18, v178, v182
	v_add_f32_e32 v19, v179, v183
	v_sub_f32_e32 v20, v178, v182
	v_sub_f32_e32 v21, v179, v183
	v_add_f32_e32 v10, v176, v18
	v_add_f32_e32 v11, v177, v19
	v_sub_f32_e32 v180, v176, v18
	v_sub_f32_e32 v181, v177, v19
	v_sub_f32_e32 v178, v16, v21
	v_add_f32_e32 v179, v17, v20
	v_add_f32_e32 v182, v16, v21
	v_sub_f32_e32 v183, v17, v20
	v_add_f32_e32 v186, v184, v24
	v_add_f32_e32 v187, v185, v25
	v_sub_f32_e32 v188, v184, v24
	v_sub_f32_e32 v189, v185, v25
	v_add_f32_e32 v190, v22, v26
	v_add_f32_e32 v191, v23, v27
	v_sub_f32_e32 v194, v22, v26
	v_sub_f32_e32 v195, v23, v27
	v_add_f32_e32 v184, v186, v190
	v_add_f32_e32 v185, v187, v191
	v_sub_f32_e32 v24, v186, v190
	v_sub_f32_e32 v25, v187, v191
	v_sub_f32_e32 v22, v188, v195
	v_add_f32_e32 v23, v189, v194
	v_add_f32_e32 v26, v188, v195
	v_sub_f32_e32 v27, v189, v194
	v_add_f32_e32 v196, v192, v30
	v_add_f32_e32 v197, v193, v31
	v_sub_f32_e32 v138, v192, v30
	v_sub_f32_e32 v139, v193, v31
	v_add_f32_e32 v98, v28, v32
	v_add_f32_e32 v99, v29, v33
	v_sub_f32_e32 v12, v28, v32
	v_sub_f32_e32 v13, v29, v33
	v_add_f32_e32 v192, v196, v98
	v_add_f32_e32 v193, v197, v99
	v_sub_f32_e32 v30, v196, v98
	v_sub_f32_e32 v31, v197, v99
	v_sub_f32_e32 v28, v138, v13
	v_add_f32_e32 v29, v139, v12
	v_add_f32_e32 v32, v138, v13
	v_sub_f32_e32 v33, v139, v12
	v_add_f32_e32 v14, v140, v172
	v_add_f32_e32 v15, v141, v173
	v_sub_f32_e32 v176, v140, v172
	v_sub_f32_e32 v177, v141, v173
	v_add_f32_e32 v16, v170, v174
	v_add_f32_e32 v17, v171, v175
	v_sub_f32_e32 v18, v170, v174
	v_sub_f32_e32 v19, v171, v175
	v_add_f32_e32 v140, v14, v16
	v_add_f32_e32 v141, v15, v17
	v_sub_f32_e32 v172, v14, v16
	v_sub_f32_e32 v173, v15, v17
	v_sub_f32_e32 v170, v176, v19
	v_add_f32_e32 v171, v177, v18
	v_add_f32_e32 v174, v176, v19
	v_sub_f32_e32 v175, v177, v18
	ds_write_b64 v1, v[10:11]
	ds_write_b64 v1, v[184:185] offset:32
	ds_write_b64 v1, v[192:193] offset:64
	ds_write_b64 v1, v[140:141] offset:96
	ds_write_b64 v1, v[178:179] offset:128
	ds_write_b64 v1, v[22:23] offset:160
	ds_write_b64 v1, v[28:29] offset:192
	ds_write_b64 v1, v[170:171] offset:224
	ds_write_b64 v1, v[180:181] offset:256
	ds_write_b64 v1, v[24:25] offset:288
	ds_write_b64 v1, v[30:31] offset:320
	ds_write_b64 v1, v[172:173] offset:352
	ds_write_b64 v1, v[182:183] offset:384
	ds_write_b64 v1, v[26:27] offset:416
	ds_write_b64 v1, v[32:33] offset:448
	ds_write_b64 v1, v[174:175] offset:480
	s_mov_b32 s38, s67
	s_mov_b32 s39, s66
	s_mov_b32 s40, s70
	s_mov_b32 s41, s66
	s_mov_b32 s38, s71
	s_mov_b32 s39, s67
	s_mov_b32 s40, s25
	s_mov_b32 s41, s71
	s_movk_i32 s24, 0x2000
	s_and_b64 vcc, exec, s[0:1]
	s_mov_b64 s[0:1], 0
	s_cbranch_vccnz .LBB0_292
	s_mov_b32 s24, 0
	s_mov_b64 s[0:1], -1
	s_waitcnt lgkmcnt(0)
	s_barrier
; template <bool INV> __device__ __forceinline__ void dft4(cf& a0, cf& a1, cf& a2, cf& a3) {
;     const cf t0 = cadd(a0, a2), t1 = csub(a0, a2), t2 = cadd(a1, a3), t3 = csub(a1, a3);
;     a0 = cadd(t0, t2); a2 = csub(t0, t2);
;     if (!INV) { a1 = {t1.x + t3.y, t1.y - t3.x}; a3 = {t1.x - t3.y, t1.y + t3.x}; }
;     else      { a1 = {t1.x - t3.y, t1.y + t3.x}; a3 = {t1.x + t3.y, t1.y - t3.x}; }
; }
; template <bool INV> __device__ __forceinline__ void dft16(cf (&a)[16]) {
; #pragma unroll
;     for (int n2 = 0; n2 < 4; ++n2) dft4<INV>(a[n2], a[4 + n2], a[8 + n2], a[12 + n2]);
; #pragma unroll
;     for (int k1 = 1; k1 < 4; ++k1)
; #pragma unroll
;         for (int n2 = 1; n2 < 4; ++n2) { const cf w = {W16C(n2 * k1), W16S(n2 * k1)};
;             a[4 * k1 + n2] = INV ? cmul(a[4 * k1 + n2], w) : cmulc(a[4 * k1 + n2], w); }
; #pragma unroll
;     for (int k1 = 0; k1 < 4; ++k1) dft4<INV>(a[4 * k1 + 0], a[4 * k1 + 1], a[4 * k1 + 2], a[4 * k1 + 3]);
; }
; template <bool INV, int LQ> __device__ __forceinline__ void fft_pass16(f32x2* X, int tid) {
;     ...
;         } else {
;             cf w = w1;
; #pragma unroll
;             for (int k = 1; k < 16; ++k) { a[k] = cmul(a[k], w); w = cmul(w, w1); }
;             dft16<true>(a);
; #pragma unroll
;             for (int k = 0; k < 16; ++k) { const int src = 4 * (k & 3) + (k >> 2); xb[k * STR] = (f32x2){a[src].x, a[src].y}; }
;         }
.LBB0_294:
	v_add_u32_e32 v2, s24, v242
	v_lshrrev_b32_e32 v2, 4, v2
	v_and_b32_e32 v0, 63, v2
	v_lshrrev_b32_e32 v2, 6, v2
	v_lshl_add_u32 v1, v2, 10, v0
	v_lshrrev_b32_e32 v2, 6, v1
	v_lshl_add_u32 v1, v2, 2, v1
	v_lshlrev_b32_e32 v1, 3, v1
	ds_read_b64 v[10:11], v1
	ds_read_b64 v[12:13], v1 offset:544
	ds_read_b64 v[14:15], v1 offset:1088
	ds_read_b64 v[16:17], v1 offset:1632
	ds_read_b64 v[18:19], v1 offset:2176
	ds_read_b64 v[20:21], v1 offset:2720
	ds_read_b64 v[22:23], v1 offset:3264
	ds_read_b64 v[24:25], v1 offset:3808
	ds_read_b64 v[26:27], v1 offset:4352
	ds_read_b64 v[28:29], v1 offset:4896
	ds_read_b64 v[30:31], v1 offset:5440
	ds_read_b64 v[32:33], v1 offset:5984
	ds_read_b64 v[106:107], v1 offset:6528
	ds_read_b64 v[108:109], v1 offset:7072
	ds_read_b64 v[110:111], v1 offset:7616
	ds_read_b64 v[112:113], v1 offset:8160
	v_cvt_f32_u32_e32 v3, v0
	v_mul_f32_e32 v3, 0x3a800000, v3
	v_sin_f32_e32 v4, v3
	v_cos_f32_e32 v3, v3
	s_waitcnt lgkmcnt(0)
	v_mul_f32_e32 v114, v12, v3
	v_mul_f32_e32 v115, v12, v4
	v_fma_f32 v114, -v13, v4, v114
	v_fmac_f32_e32 v115, v13, v3
	v_mul_f32_e32 v5, v3, v3
	v_mul_f32_e32 v6, v3, v4
	v_fma_f32 v5, -v4, v4, v5
	v_fmac_f32_e32 v6, v4, v3
	v_mul_f32_e32 v116, v14, v5
	v_mul_f32_e32 v117, v14, v6
	v_fma_f32 v116, -v15, v6, v116
	v_fmac_f32_e32 v117, v15, v5
	v_mul_f32_e32 v7, v5, v3
	v_mul_f32_e32 v8, v5, v4
	v_fma_f32 v7, -v6, v4, v7
	v_fmac_f32_e32 v8, v6, v3
	v_mul_f32_e32 v118, v16, v7
	v_mul_f32_e32 v119, v16, v8
	v_fma_f32 v118, -v17, v8, v118
	v_fmac_f32_e32 v119, v17, v7
	v_mul_f32_e32 v5, v7, v3
	v_mul_f32_e32 v6, v7, v4
	v_fma_f32 v5, -v8, v4, v5
	v_fmac_f32_e32 v6, v8, v3
	v_mul_f32_e32 v120, v18, v5
	v_mul_f32_e32 v121, v18, v6
	v_fma_f32 v120, -v19, v6, v120
	v_fmac_f32_e32 v121, v19, v5
	v_mul_f32_e32 v7, v5, v3
	v_mul_f32_e32 v8, v5, v4
	v_fma_f32 v7, -v6, v4, v7
	v_fmac_f32_e32 v8, v6, v3
	v_mul_f32_e32 v122, v20, v7
	v_mul_f32_e32 v123, v20, v8
	v_fma_f32 v122, -v21, v8, v122
	v_fmac_f32_e32 v123, v21, v7
	v_mul_f32_e32 v5, v7, v3
	v_mul_f32_e32 v6, v7, v4
	v_fma_f32 v5, -v8, v4, v5
	v_fmac_f32_e32 v6, v8, v3
	v_mul_f32_e32 v124, v22, v5
	v_mul_f32_e32 v125, v22, v6
	v_fma_f32 v124, -v23, v6, v124
	v_fmac_f32_e32 v125, v23, v5
	v_mul_f32_e32 v7, v5, v3
	v_mul_f32_e32 v8, v5, v4
	v_fma_f32 v7, -v6, v4, v7
	v_fmac_f32_e32 v8, v6, v3
	v_mul_f32_e32 v126, v24, v7
	v_mul_f32_e32 v127, v24, v8
	v_fma_f32 v126, -v25, v8, v126
	v_fmac_f32_e32 v127, v25, v7
	v_mul_f32_e32 v5, v7, v3
	v_mul_f32_e32 v6, v7, v4
	v_fma_f32 v5, -v8, v4, v5
	v_fmac_f32_e32 v6, v8, v3
	v_mul_f32_e32 v128, v26, v5
	v_mul_f32_e32 v129, v26, v6
	v_fma_f32 v128, -v27, v6, v128
	v_fmac_f32_e32 v129, v27, v5
	v_mul_f32_e32 v7, v5, v3
	v_mul_f32_e32 v8, v5, v4
	v_fma_f32 v7, -v6, v4, v7
	v_fmac_f32_e32 v8, v6, v3
	v_mul_f32_e32 v130, v28, v7
	v_mul_f32_e32 v131, v28, v8
	v_fma_f32 v130, -v29, v8, v130
	v_fmac_f32_e32 v131, v29, v7
	v_mul_f32_e32 v5, v7, v3
	v_mul_f32_e32 v6, v7, v4
	v_fma_f32 v5, -v8, v4, v5
	v_fmac_f32_e32 v6, v8, v3
	v_mul_f32_e32 v132, v30, v5
	v_mul_f32_e32 v133, v30, v6
	v_fma_f32 v132, -v31, v6, v132
	v_fmac_f32_e32 v133, v31, v5
	v_mul_f32_e32 v7, v5, v3
	v_mul_f32_e32 v8, v5, v4
	v_fma_f32 v7, -v6, v4, v7
	v_fmac_f32_e32 v8, v6, v3
	v_mul_f32_e32 v134, v32, v7
	v_mul_f32_e32 v135, v32, v8
	v_fma_f32 v134, -v33, v8, v134
	v_fmac_f32_e32 v135, v33, v7
	v_mul_f32_e32 v5, v7, v3
	v_mul_f32_e32 v6, v7, v4
	v_fma_f32 v5, -v8, v4, v5
	v_fmac_f32_e32 v6, v8, v3
	v_mul_f32_e32 v136, v106, v5
	v_mul_f32_e32 v137, v106, v6
	v_fma_f32 v136, -v107, v6, v136
	v_fmac_f32_e32 v137, v107, v5
	v_mul_f32_e32 v7, v5, v3
	v_mul_f32_e32 v8, v5, v4
	v_fma_f32 v7, -v6, v4, v7
	v_fmac_f32_e32 v8, v6, v3
	v_mul_f32_e32 v138, v108, v7
	v_mul_f32_e32 v139, v108, v8
	v_fma_f32 v138, -v109, v8, v138
	v_fmac_f32_e32 v139, v109, v7
	v_mul_f32_e32 v5, v7, v3
	v_mul_f32_e32 v6, v7, v4
	v_fma_f32 v5, -v8, v4, v5
	v_fmac_f32_e32 v6, v8, v3
	v_mul_f32_e32 v140, v110, v5
	v_mul_f32_e32 v141, v110, v6
	v_fma_f32 v140, -v111, v6, v140
	v_fmac_f32_e32 v141, v111, v5
	v_mul_f32_e32 v7, v5, v3
	v_mul_f32_e32 v8, v5, v4
	v_fma_f32 v7, -v6, v4, v7
	v_fmac_f32_e32 v8, v6, v3
	v_mul_f32_e32 v142, v112, v7
	v_mul_f32_e32 v143, v112, v8
	v_fma_f32 v142, -v113, v8, v142
	v_fmac_f32_e32 v143, v113, v7
	v_add_f32_e32 v98, v10, v128
	v_add_f32_e32 v99, v11, v129
	v_sub_f32_e32 v12, v10, v128
	v_sub_f32_e32 v13, v11, v129
	v_add_f32_e32 v14, v120, v136
	v_add_f32_e32 v15, v121, v137
	v_sub_f32_e32 v16, v120, v136
	v_sub_f32_e32 v17, v121, v137
	v_add_f32_e32 v10, v98, v14
	v_add_f32_e32 v11, v99, v15
	v_sub_f32_e32 v128, v98, v14
	v_sub_f32_e32 v129, v99, v15
	v_sub_f32_e32 v120, v12, v17
	v_add_f32_e32 v121, v13, v16
	v_add_f32_e32 v136, v12, v17
	v_sub_f32_e32 v137, v13, v16
	v_add_f32_e32 v18, v114, v130
	v_add_f32_e32 v19, v115, v131
	v_sub_f32_e32 v20, v114, v130
	v_sub_f32_e32 v21, v115, v131
	v_add_f32_e32 v22, v122, v138
	v_add_f32_e32 v23, v123, v139
	v_sub_f32_e32 v24, v122, v138
	v_sub_f32_e32 v25, v123, v139
	v_add_f32_e32 v114, v18, v22
	v_add_f32_e32 v115, v19, v23
	v_sub_f32_e32 v130, v18, v22
	v_sub_f32_e32 v131, v19, v23
	v_sub_f32_e32 v122, v20, v25
	v_add_f32_e32 v123, v21, v24
	v_add_f32_e32 v138, v20, v25
	v_sub_f32_e32 v139, v21, v24
	v_add_f32_e32 v26, v116, v132
	v_add_f32_e32 v27, v117, v133
	v_sub_f32_e32 v28, v116, v132
	v_sub_f32_e32 v29, v117, v133
	v_add_f32_e32 v30, v124, v140
	v_add_f32_e32 v31, v125, v141
	v_sub_f32_e32 v32, v124, v140
	v_sub_f32_e32 v33, v125, v141
	v_add_f32_e32 v116, v26, v30
	v_add_f32_e32 v117, v27, v31
	v_sub_f32_e32 v132, v26, v30
	v_sub_f32_e32 v133, v27, v31
	v_sub_f32_e32 v124, v28, v33
; template <bool INV> __device__ __forceinline__ void dft16(cf (&a)[16]) {
; #pragma unroll
;     for (int n2 = 0; n2 < 4; ++n2) dft4<INV>(a[n2], a[4 + n2], a[8 + n2], a[12 + n2]);
; #pragma unroll
;     for (int k1 = 1; k1 < 4; ++k1)
; #pragma unroll
;         for (int n2 = 1; n2 < 4; ++n2) { const cf w = {W16C(n2 * k1), W16S(n2 * k1)};
;             a[4 * k1 + n2] = INV ? cmul(a[4 * k1 + n2], w) : cmulc(a[4 * k1 + n2], w); }
; #pragma unroll
;     for (int k1 = 0; k1 < 4; ++k1) dft4<INV>(a[4 * k1 + 0], a[4 * k1 + 1], a[4 * k1 + 2], a[4 * k1 + 3]);
; }
; template <bool INV, int LQ> __device__ __forceinline__ void fft_pass16(f32x2* X, int tid) {
;     ...
;         } else {
;             cf w = w1;
; #pragma unroll
;             for (int k = 1; k < 16; ++k) { a[k] = cmul(a[k], w); w = cmul(w, w1); }
;             dft16<true>(a);
; #pragma unroll
;             for (int k = 0; k < 16; ++k) { const int src = 4 * (k & 3) + (k >> 2); xb[k * STR] = (f32x2){a[src].x, a[src].y}; }
;         }
	v_add_f32_e32 v125, v29, v32
	v_add_f32_e32 v140, v28, v33
	v_sub_f32_e32 v141, v29, v32
	v_add_f32_e32 v106, v118, v134
	v_add_f32_e32 v107, v119, v135
	v_sub_f32_e32 v108, v118, v134
	v_sub_f32_e32 v109, v119, v135
	v_add_f32_e32 v110, v126, v142
	v_add_f32_e32 v111, v127, v143
	v_sub_f32_e32 v112, v126, v142
	v_sub_f32_e32 v113, v127, v143
	v_add_f32_e32 v118, v106, v110
	v_add_f32_e32 v119, v107, v111
	v_sub_f32_e32 v134, v106, v110
	v_sub_f32_e32 v135, v107, v111
	v_sub_f32_e32 v126, v108, v113
	v_add_f32_e32 v127, v109, v112
	v_add_f32_e32 v142, v108, v113
	v_sub_f32_e32 v143, v109, v112
	v_mul_f32_e32 v98, s67, v122
	v_mul_f32_e32 v99, s67, v123
	v_fma_f32 v98, -v123, s66, v98
	v_fmac_f32_e32 v99, s66, v122
	v_sub_f32_e32 v12, v124, v125
	v_add_f32_e32 v13, v124, v125
	v_mul_f32_e32 v12, s70, v12
	v_mul_f32_e32 v13, s70, v13
	v_mul_f32_e32 v14, s66, v126
	v_mul_f32_e32 v15, s66, v127
	v_fma_f32 v14, -v127, s67, v14
	v_fmac_f32_e32 v15, s67, v126
	v_sub_f32_e32 v16, v130, v131
	v_add_f32_e32 v17, v130, v131
	v_mul_f32_e32 v16, s70, v16
	v_mul_f32_e32 v17, s70, v17
	v_xor_b32_e32 v18, 0x80000000, v133
	v_mov_b32_e32 v19, v132
	v_add_f32_e32 v20, v134, v135
	v_sub_f32_e32 v21, v134, v135
	v_mul_f32_e32 v20, s71, v20
	v_mul_f32_e32 v21, s70, v21
	v_mul_f32_e32 v22, s66, v138
	v_mul_f32_e32 v23, s66, v139
	v_fma_f32 v22, -v139, s67, v22
	v_fmac_f32_e32 v23, s67, v138
	v_add_f32_e32 v24, v140, v141
	v_sub_f32_e32 v25, v140, v141
	v_mul_f32_e32 v24, s71, v24
	v_mul_f32_e32 v25, s70, v25
	v_mul_f32_e32 v26, s67, v142
	v_mul_f32_e32 v27, s67, v143
	v_fma_f32 v26, -v143, s66, v26
	v_fmac_f32_e32 v27, s66, v142
	v_xor_b32_e32 v26, 0x80000000, v26
	v_xor_b32_e32 v27, 0x80000000, v27
	v_add_f32_e32 v28, v10, v116
	v_add_f32_e32 v29, v11, v117
	v_sub_f32_e32 v30, v10, v116
	v_sub_f32_e32 v31, v11, v117
	v_add_f32_e32 v32, v114, v118
	v_add_f32_e32 v33, v115, v119
	v_sub_f32_e32 v106, v114, v118
	v_sub_f32_e32 v107, v115, v119
	v_add_f32_e32 v10, v28, v32
	v_add_f32_e32 v11, v29, v33
	v_sub_f32_e32 v116, v28, v32
	v_sub_f32_e32 v117, v29, v33
	v_sub_f32_e32 v114, v30, v107
	v_add_f32_e32 v115, v31, v106
	v_add_f32_e32 v118, v30, v107
	v_sub_f32_e32 v119, v31, v106
	v_add_f32_e32 v108, v120, v12
	v_add_f32_e32 v109, v121, v13
	v_sub_f32_e32 v110, v120, v12
	v_sub_f32_e32 v111, v121, v13
	v_add_f32_e32 v112, v98, v14
	v_add_f32_e32 v113, v99, v15
	v_sub_f32_e32 v122, v98, v14
	v_sub_f32_e32 v123, v99, v15
	v_add_f32_e32 v120, v108, v112
	v_add_f32_e32 v121, v109, v113
	v_sub_f32_e32 v12, v108, v112
	v_sub_f32_e32 v13, v109, v113
	v_sub_f32_e32 v98, v110, v123
	v_add_f32_e32 v99, v111, v122
	v_add_f32_e32 v14, v110, v123
	v_sub_f32_e32 v15, v111, v122
	v_add_f32_e32 v124, v128, v18
	v_add_f32_e32 v125, v129, v19
	v_sub_f32_e32 v126, v128, v18
	v_sub_f32_e32 v127, v129, v19
	v_add_f32_e32 v130, v16, v20
	v_add_f32_e32 v131, v17, v21
	v_sub_f32_e32 v132, v16, v20
	v_sub_f32_e32 v133, v17, v21
	v_add_f32_e32 v128, v124, v130
	v_add_f32_e32 v129, v125, v131
	v_sub_f32_e32 v18, v124, v130
	v_sub_f32_e32 v19, v125, v131
	v_sub_f32_e32 v16, v126, v133
	v_add_f32_e32 v17, v127, v132
	v_add_f32_e32 v20, v126, v133
	v_sub_f32_e32 v21, v127, v132
	v_add_f32_e32 v134, v136, v24
	v_add_f32_e32 v135, v137, v25
	v_sub_f32_e32 v138, v136, v24
	v_sub_f32_e32 v139, v137, v25
	v_add_f32_e32 v140, v22, v26
	v_add_f32_e32 v141, v23, v27
	v_sub_f32_e32 v142, v22, v26
	v_sub_f32_e32 v143, v23, v27
	v_add_f32_e32 v136, v134, v140
	v_add_f32_e32 v137, v135, v141
	v_sub_f32_e32 v24, v134, v140
	v_sub_f32_e32 v25, v135, v141
	v_sub_f32_e32 v22, v138, v143
	v_add_f32_e32 v23, v139, v142
	v_add_f32_e32 v26, v138, v143
	v_sub_f32_e32 v27, v139, v142
	ds_write_b64 v1, v[10:11]
	ds_write_b64 v1, v[120:121] offset:544
	ds_write_b64 v1, v[128:129] offset:1088
	ds_write_b64 v1, v[136:137] offset:1632
	ds_write_b64 v1, v[114:115] offset:2176
	ds_write_b64 v1, v[98:99] offset:2720
	ds_write_b64 v1, v[16:17] offset:3264
	ds_write_b64 v1, v[22:23] offset:3808
	ds_write_b64 v1, v[116:117] offset:4352
	ds_write_b64 v1, v[12:13] offset:4896
	ds_write_b64 v1, v[18:19] offset:5440
	ds_write_b64 v1, v[24:25] offset:5984
	ds_write_b64 v1, v[118:119] offset:6528
	ds_write_b64 v1, v[14:15] offset:7072
	ds_write_b64 v1, v[20:21] offset:7616
	ds_write_b64 v1, v[26:27] offset:8160
	s_mov_b32 s38, s67
	s_mov_b32 s39, s66
	s_mov_b32 s40, s70
	s_mov_b32 s41, s66
	s_mov_b32 s38, s71
	s_mov_b32 s39, s67
	s_mov_b32 s40, s25
	s_mov_b32 s41, s71
	s_movk_i32 s24, 0x2000
	s_and_b64 vcc, exec, s[0:1]
	s_mov_b64 s[0:1], 0
	s_cbranch_vccnz .LBB0_294
	s_mov_b32 s24, 0
	s_mov_b64 s[0:1], -1
	s_waitcnt lgkmcnt(0)
	s_barrier
; template <bool INV, int LQ> __device__ __forceinline__ void fft_pass16(f32x2* X, int tid) {
;     ...
;         const int g = tid + 512 * gg, blk = g >> LQ, i = g & (q - 1), base = (blk << (LQ + 4)) + i;
;         f32x2* xb = X + fidx(base);
;         cf a[16];
; #pragma unroll
;         for (int j = 0; j < 16; ++j) { const f32x2 v = xb[j * STR]; a[j] = {v.x, v.y}; }
;         const float rev = (float)i * (1.f / (float)(16 << LQ));
;         const cf w1 = {__builtin_amdgcn_cosf(rev), __builtin_amdgcn_sinf(rev)};
;         if (!INV) {
;             dft16<false>(a);
;             cf w = w1;
; #pragma unroll
;             for (int k = 1; k < 16; ++k) { const int src = 4 * (k & 3) + (k >> 2);
;                 const cf y = cmulc(a[src], w); xb[k * STR] = (f32x2){y.x, y.y}; w = cmul(w, w1); }
;             xb[0] = (f32x2){a[0].x, a[0].y};
;         } else {
;             cf w = w1;
; #pragma unroll
;             for (int k = 1; k < 16; ++k) { a[k] = cmul(a[k], w); w = cmul(w, w1); }
;             dft16<true>(a);
; #pragma unroll
;             for (int k = 0; k < 16; ++k) { const int src = 4 * (k & 3) + (k >> 2); xb[k * STR] = (f32x2){a[src].x, a[src].y}; }
;         }
.LBB0_296:
	v_add_u32_e32 v0, s24, v240
	v_and_b32_e32 v0, 0x3ff, v0
	v_lshrrev_b32_e32 v1, 6, v0
	v_lshl_add_u32 v1, v1, 2, v0
	v_lshlrev_b32_e32 v1, 3, v1
	v_add_u32_e32 v2, 0x11000, v1
	ds_read_b64 v[42:43], v1
	ds_read_b64 v[44:45], v1 offset:8704
	ds_read_b64 v[46:47], v1 offset:17408
	ds_read_b64 v[48:49], v1 offset:26112
	ds_read_b64 v[50:51], v1 offset:34816
	ds_read_b64 v[52:53], v1 offset:43520
	ds_read_b64 v[54:55], v1 offset:52224
	ds_read_b64 v[56:57], v1 offset:60928
	ds_read_b64 v[58:59], v2
	ds_read_b64 v[60:61], v2 offset:8704
	ds_read_b64 v[62:63], v2 offset:17408
	ds_read_b64 v[64:65], v2 offset:26112
	ds_read_b64 v[66:67], v2 offset:34816
	ds_read_b64 v[68:69], v2 offset:43520
	ds_read_b64 v[70:71], v2 offset:52224
	ds_read_b64 v[72:73], v2 offset:60928
	v_cvt_f32_u32_e32 v3, v0
	v_mul_f32_e32 v3, 0x38800000, v3
	v_sin_f32_e32 v4, v3
	v_cos_f32_e32 v3, v3
	s_waitcnt lgkmcnt(0)
	v_mul_f32_e32 v74, v44, v3
	v_mul_f32_e32 v75, v44, v4
	v_fma_f32 v74, -v45, v4, v74
	v_fmac_f32_e32 v75, v45, v3
	v_mul_f32_e32 v5, v3, v3
	v_mul_f32_e32 v6, v3, v4
	v_fma_f32 v5, -v4, v4, v5
	v_fmac_f32_e32 v6, v4, v3
	v_mul_f32_e32 v76, v46, v5
	v_mul_f32_e32 v77, v46, v6
	v_fma_f32 v76, -v47, v6, v76
	v_fmac_f32_e32 v77, v47, v5
	v_mul_f32_e32 v7, v5, v3
	v_mul_f32_e32 v8, v5, v4
	v_fma_f32 v7, -v6, v4, v7
	v_fmac_f32_e32 v8, v6, v3
	v_mul_f32_e32 v78, v48, v7
	v_mul_f32_e32 v79, v48, v8
	v_fma_f32 v78, -v49, v8, v78
	v_fmac_f32_e32 v79, v49, v7
	v_mul_f32_e32 v5, v7, v3
	v_mul_f32_e32 v6, v7, v4
	v_fma_f32 v5, -v8, v4, v5
	v_fmac_f32_e32 v6, v8, v3
	v_mul_f32_e32 v80, v50, v5
	v_mul_f32_e32 v81, v50, v6
	v_fma_f32 v80, -v51, v6, v80
	v_fmac_f32_e32 v81, v51, v5
	v_mul_f32_e32 v7, v5, v3
	v_mul_f32_e32 v8, v5, v4
	v_fma_f32 v7, -v6, v4, v7
	v_fmac_f32_e32 v8, v6, v3
	v_mul_f32_e32 v82, v52, v7
	v_mul_f32_e32 v83, v52, v8
	v_fma_f32 v82, -v53, v8, v82
	v_fmac_f32_e32 v83, v53, v7
	v_mul_f32_e32 v5, v7, v3
	v_mul_f32_e32 v6, v7, v4
	v_fma_f32 v5, -v8, v4, v5
	v_fmac_f32_e32 v6, v8, v3
	v_mul_f32_e32 v84, v54, v5
	v_mul_f32_e32 v85, v54, v6
	v_fma_f32 v84, -v55, v6, v84
	v_fmac_f32_e32 v85, v55, v5
	v_mul_f32_e32 v7, v5, v3
	v_mul_f32_e32 v8, v5, v4
	v_fma_f32 v7, -v6, v4, v7
	v_fmac_f32_e32 v8, v6, v3
	v_mul_f32_e32 v86, v56, v7
	v_mul_f32_e32 v87, v56, v8
	v_fma_f32 v86, -v57, v8, v86
	v_fmac_f32_e32 v87, v57, v7
	v_mul_f32_e32 v5, v7, v3
	v_mul_f32_e32 v6, v7, v4
	v_fma_f32 v5, -v8, v4, v5
	v_fmac_f32_e32 v6, v8, v3
	v_mul_f32_e32 v18, v58, v5
	v_mul_f32_e32 v19, v58, v6
	v_fma_f32 v18, -v59, v6, v18
	v_fmac_f32_e32 v19, v59, v5
	v_mul_f32_e32 v7, v5, v3
	v_mul_f32_e32 v8, v5, v4
	v_fma_f32 v7, -v6, v4, v7
	v_fmac_f32_e32 v8, v6, v3
	v_mul_f32_e32 v20, v60, v7
	v_mul_f32_e32 v21, v60, v8
	v_fma_f32 v20, -v61, v8, v20
	v_fmac_f32_e32 v21, v61, v7
	v_mul_f32_e32 v5, v7, v3
	v_mul_f32_e32 v6, v7, v4
	v_fma_f32 v5, -v8, v4, v5
	v_fmac_f32_e32 v6, v8, v3
	v_mul_f32_e32 v22, v62, v5
	v_mul_f32_e32 v23, v62, v6
	v_fma_f32 v22, -v63, v6, v22
	v_fmac_f32_e32 v23, v63, v5
	v_mul_f32_e32 v7, v5, v3
	v_mul_f32_e32 v8, v5, v4
	v_fma_f32 v7, -v6, v4, v7
	v_fmac_f32_e32 v8, v6, v3
	v_mul_f32_e32 v24, v64, v7
	v_mul_f32_e32 v25, v64, v8
	v_fma_f32 v24, -v65, v8, v24
	v_fmac_f32_e32 v25, v65, v7
	v_mul_f32_e32 v5, v7, v3
	v_mul_f32_e32 v6, v7, v4
	v_fma_f32 v5, -v8, v4, v5
	v_fmac_f32_e32 v6, v8, v3
	v_mul_f32_e32 v26, v66, v5
	v_mul_f32_e32 v27, v66, v6
	v_fma_f32 v26, -v67, v6, v26
	v_fmac_f32_e32 v27, v67, v5
	v_mul_f32_e32 v7, v5, v3
	v_mul_f32_e32 v8, v5, v4
	v_fma_f32 v7, -v6, v4, v7
	v_fmac_f32_e32 v8, v6, v3
	v_mul_f32_e32 v28, v68, v7
	v_mul_f32_e32 v29, v68, v8
	v_fma_f32 v28, -v69, v8, v28
	v_fmac_f32_e32 v29, v69, v7
	v_mul_f32_e32 v5, v7, v3
	v_mul_f32_e32 v6, v7, v4
	v_fma_f32 v5, -v8, v4, v5
	v_fmac_f32_e32 v6, v8, v3
	v_mul_f32_e32 v30, v70, v5
	v_mul_f32_e32 v31, v70, v6
	v_fma_f32 v30, -v71, v6, v30
	v_fmac_f32_e32 v31, v71, v5
	v_mul_f32_e32 v7, v5, v3
	v_mul_f32_e32 v8, v5, v4
	v_fma_f32 v7, -v6, v4, v7
	v_fmac_f32_e32 v8, v6, v3
	v_mul_f32_e32 v32, v72, v7
	v_mul_f32_e32 v33, v72, v8
	v_fma_f32 v32, -v73, v8, v32
	v_fmac_f32_e32 v33, v73, v7
	v_add_f32_e32 v44, v42, v18
	v_add_f32_e32 v45, v43, v19
	v_sub_f32_e32 v46, v42, v18
	v_sub_f32_e32 v47, v43, v19
	v_add_f32_e32 v48, v80, v26
	v_add_f32_e32 v49, v81, v27
	v_sub_f32_e32 v50, v80, v26
	v_sub_f32_e32 v51, v81, v27
	v_add_f32_e32 v42, v44, v48
	v_add_f32_e32 v43, v45, v49
	v_sub_f32_e32 v18, v44, v48
	v_sub_f32_e32 v19, v45, v49
	v_sub_f32_e32 v80, v46, v51
	v_add_f32_e32 v81, v47, v50
	v_add_f32_e32 v26, v46, v51
	v_sub_f32_e32 v27, v47, v50
	v_add_f32_e32 v52, v74, v20
	v_add_f32_e32 v53, v75, v21
	v_sub_f32_e32 v54, v74, v20
	v_sub_f32_e32 v55, v75, v21
	v_add_f32_e32 v56, v82, v28
	v_add_f32_e32 v57, v83, v29
	v_sub_f32_e32 v58, v82, v28
	v_sub_f32_e32 v59, v83, v29
	v_add_f32_e32 v74, v52, v56
	v_add_f32_e32 v75, v53, v57
	v_sub_f32_e32 v20, v52, v56
	v_sub_f32_e32 v21, v53, v57
	v_sub_f32_e32 v82, v54, v59
	v_add_f32_e32 v83, v55, v58
	v_add_f32_e32 v28, v54, v59
	v_sub_f32_e32 v29, v55, v58
	v_add_f32_e32 v60, v76, v22
	v_add_f32_e32 v61, v77, v23
	v_sub_f32_e32 v62, v76, v22
	v_sub_f32_e32 v63, v77, v23
	v_add_f32_e32 v64, v84, v30
	v_add_f32_e32 v65, v85, v31
; template <bool INV, int LQ> __device__ __forceinline__ void fft_pass16(f32x2* X, int tid) {
;     ...
;             dft16<true>(a);
; #pragma unroll
;             for (int k = 0; k < 16; ++k) { const int src = 4 * (k & 3) + (k >> 2); xb[k * STR] = (f32x2){a[src].x, a[src].y}; }
;         }
; __device__ __forceinline__ float block_sum(float v, float* red, int lane, int wid) {
;     v = wave_sum(v); __syncthreads(); if (lane == 0) red[wid] = v; __syncthreads();
;     float s = 0.f;
; #pragma unroll
;     for (int i = 0; i < 8; ++i) s += red[i];
;     return s;
	v_sub_f32_e32 v66, v84, v30
	v_sub_f32_e32 v67, v85, v31
	v_add_f32_e32 v76, v60, v64
	v_add_f32_e32 v77, v61, v65
	v_sub_f32_e32 v22, v60, v64
	v_sub_f32_e32 v23, v61, v65
	v_sub_f32_e32 v84, v62, v67
	v_add_f32_e32 v85, v63, v66
	v_add_f32_e32 v30, v62, v67
	v_sub_f32_e32 v31, v63, v66
	v_add_f32_e32 v68, v78, v24
	v_add_f32_e32 v69, v79, v25
	v_sub_f32_e32 v70, v78, v24
	v_sub_f32_e32 v71, v79, v25
	v_add_f32_e32 v72, v86, v32
	v_add_f32_e32 v73, v87, v33
	v_sub_f32_e32 v44, v86, v32
	v_sub_f32_e32 v45, v87, v33
	v_add_f32_e32 v78, v68, v72
	v_add_f32_e32 v79, v69, v73
	v_sub_f32_e32 v24, v68, v72
	v_sub_f32_e32 v25, v69, v73
	v_sub_f32_e32 v86, v70, v45
	v_add_f32_e32 v87, v71, v44
	v_add_f32_e32 v32, v70, v45
	v_sub_f32_e32 v33, v71, v44
	v_mul_f32_e32 v46, s67, v82
	v_mul_f32_e32 v47, s67, v83
	v_fma_f32 v46, -v83, s66, v46
	v_fmac_f32_e32 v47, s66, v82
	v_sub_f32_e32 v48, v84, v85
	v_add_f32_e32 v49, v84, v85
	v_mul_f32_e32 v48, s70, v48
	v_mul_f32_e32 v49, s70, v49
	v_mul_f32_e32 v50, s66, v86
	v_mul_f32_e32 v51, s66, v87
	v_fma_f32 v50, -v87, s67, v50
	v_fmac_f32_e32 v51, s67, v86
	v_sub_f32_e32 v52, v20, v21
	v_add_f32_e32 v53, v20, v21
	v_mul_f32_e32 v52, s70, v52
	v_mul_f32_e32 v53, s70, v53
	v_xor_b32_e32 v54, 0x80000000, v23
	v_mov_b32_e32 v55, v22
	v_add_f32_e32 v56, v24, v25
	v_sub_f32_e32 v57, v24, v25
	v_mul_f32_e32 v56, s71, v56
	v_mul_f32_e32 v57, s70, v57
	v_mul_f32_e32 v58, s66, v28
	v_mul_f32_e32 v59, s66, v29
	v_fma_f32 v58, -v29, s67, v58
	v_fmac_f32_e32 v59, s67, v28
	v_add_f32_e32 v60, v30, v31
	v_sub_f32_e32 v61, v30, v31
	v_mul_f32_e32 v60, s71, v60
	v_mul_f32_e32 v61, s70, v61
	v_mul_f32_e32 v62, s67, v32
	v_mul_f32_e32 v63, s67, v33
	v_fma_f32 v62, -v33, s66, v62
	v_fmac_f32_e32 v63, s66, v32
	v_xor_b32_e32 v62, 0x80000000, v62
	v_xor_b32_e32 v63, 0x80000000, v63
	v_add_f32_e32 v64, v42, v76
	v_add_f32_e32 v65, v43, v77
	v_sub_f32_e32 v66, v42, v76
	v_sub_f32_e32 v67, v43, v77
	v_add_f32_e32 v68, v74, v78
	v_add_f32_e32 v69, v75, v79
	v_sub_f32_e32 v70, v74, v78
	v_sub_f32_e32 v71, v75, v79
	v_add_f32_e32 v42, v64, v68
	v_add_f32_e32 v43, v65, v69
	v_sub_f32_e32 v76, v64, v68
	v_sub_f32_e32 v77, v65, v69
	v_sub_f32_e32 v74, v66, v71
	v_add_f32_e32 v75, v67, v70
	v_add_f32_e32 v78, v66, v71
	v_sub_f32_e32 v79, v67, v70
	v_add_f32_e32 v72, v80, v48
	v_add_f32_e32 v73, v81, v49
	v_sub_f32_e32 v44, v80, v48
	v_sub_f32_e32 v45, v81, v49
	v_add_f32_e32 v82, v46, v50
	v_add_f32_e32 v83, v47, v51
	v_sub_f32_e32 v84, v46, v50
	v_sub_f32_e32 v85, v47, v51
	v_add_f32_e32 v80, v72, v82
	v_add_f32_e32 v81, v73, v83
	v_sub_f32_e32 v48, v72, v82
	v_sub_f32_e32 v49, v73, v83
	v_sub_f32_e32 v46, v44, v85
	v_add_f32_e32 v47, v45, v84
	v_add_f32_e32 v50, v44, v85
	v_sub_f32_e32 v51, v45, v84
	v_add_f32_e32 v86, v18, v54
	v_add_f32_e32 v87, v19, v55
	v_sub_f32_e32 v20, v18, v54
	v_sub_f32_e32 v21, v19, v55
	v_add_f32_e32 v22, v52, v56
	v_add_f32_e32 v23, v53, v57
	v_sub_f32_e32 v24, v52, v56
	v_sub_f32_e32 v25, v53, v57
	v_add_f32_e32 v18, v86, v22
	v_add_f32_e32 v19, v87, v23
	v_sub_f32_e32 v54, v86, v22
	v_sub_f32_e32 v55, v87, v23
	v_sub_f32_e32 v52, v20, v25
	v_add_f32_e32 v53, v21, v24
	v_add_f32_e32 v56, v20, v25
	v_sub_f32_e32 v57, v21, v24
	v_add_f32_e32 v28, v26, v60
	v_add_f32_e32 v29, v27, v61
	v_sub_f32_e32 v30, v26, v60
	v_sub_f32_e32 v31, v27, v61
	v_add_f32_e32 v32, v58, v62
	v_add_f32_e32 v33, v59, v63
	v_sub_f32_e32 v64, v58, v62
	v_sub_f32_e32 v65, v59, v63
	v_add_f32_e32 v26, v28, v32
	v_add_f32_e32 v27, v29, v33
	v_sub_f32_e32 v60, v28, v32
	v_sub_f32_e32 v61, v29, v33
	v_sub_f32_e32 v58, v30, v65
	v_add_f32_e32 v59, v31, v64
	v_add_f32_e32 v62, v30, v65
	v_sub_f32_e32 v63, v31, v64
	ds_write_b64 v1, v[42:43]
	ds_write_b64 v1, v[80:81] offset:8704
	ds_write_b64 v1, v[18:19] offset:17408
	ds_write_b64 v1, v[26:27] offset:26112
	ds_write_b64 v1, v[74:75] offset:34816
	ds_write_b64 v1, v[46:47] offset:43520
	ds_write_b64 v1, v[52:53] offset:52224
	ds_write_b64 v1, v[58:59] offset:60928
	ds_write_b64 v2, v[76:77]
	ds_write_b64 v2, v[48:49] offset:8704
	ds_write_b64 v2, v[54:55] offset:17408
	ds_write_b64 v2, v[60:61] offset:26112
	ds_write_b64 v2, v[78:79] offset:34816
	ds_write_b64 v2, v[50:51] offset:43520
	ds_write_b64 v2, v[56:57] offset:52224
	ds_write_b64 v2, v[62:63] offset:60928
	s_mov_b32 s38, s67
	s_mov_b32 s39, s66
	s_mov_b32 s94, s70
	s_mov_b32 s95, s66
	s_mov_b32 s74, s71
	s_mov_b32 s75, s67
	s_mov_b32 s40, s25
	s_mov_b32 s41, s71
	s_movk_i32 s24, 0x200
	s_and_b64 vcc, exec, s[0:1]
	s_mov_b64 s[0:1], 0
	s_cbranch_vccnz .LBB0_296
	ds_bpermute_b32 v0, v206, v241
	v_cmp_eq_u32_e32 vcc, 0, v239
	s_waitcnt lgkmcnt(0)
	s_barrier
	v_add_f32_e32 v0, v241, v0
	ds_bpermute_b32 v1, v207, v0
	s_waitcnt lgkmcnt(0)
	s_barrier
	v_add_f32_e32 v0, v0, v1
	ds_bpermute_b32 v1, v208, v0
	s_waitcnt lgkmcnt(0)
	v_add_f32_e32 v0, v0, v1
	ds_bpermute_b32 v1, v209, v0
	s_waitcnt lgkmcnt(0)
	v_add_f32_e32 v0, v0, v1
	ds_bpermute_b32 v1, v229, v0
	s_waitcnt lgkmcnt(0)
	v_add_f32_e32 v0, v0, v1
	ds_bpermute_b32 v1, v230, v0
	s_and_saveexec_b64 s[0:1], vcc
	s_cbranch_execz .LBB0_299
	v_readlane_b32 s4, v252, 0
	s_waitcnt lgkmcnt(0)
	v_add_f32_e32 v0, v0, v1
	v_mov_b32_e32 v1, s4
	ds_write_b32 v1, v0
